# attn_d (MLA attention) phase also rewritten by hand as ping-pong pipeline (q RMSNorm+RoPE in registers, K tile from two sources)
# speedup vs baseline: 1.0521x; 1.0279x over previous
; #define LAS __attribute__((address_space(3)))
; DI int otid() { int t = threadIdx.x; asm volatile("" : "+v"(t)); return t; }
; template <int DQK, int KA8, int DV, bool BIAS, bool JOINT>
; DI void attn_core(LAS unsigned char* lds, const bf16_t* Qrow, const bf16_t* KpA, int ldkA, const bf16_t* KpB, int ldkB, const bf16_t* Vp, int ldv,
;                   int qb, int wid, int lane, const float* qng  , f32x16 (&O)[DV / 32]) {
;     constexpr int KROW = DQK * 2 + 16, VROW = DV * 2 + 64  , KC = DQK / 8, VC = DV / 8, NKC = 64 * KC, NVC = 64 * VC, NL = (NKC + NVC) / 512, STG = 64 * (KROW + VROW);
;     static_assert(NKC % 512 == 0 && NVC % 512 == 0, "loader split");
;     const int tid = otid(), l32 = lane & 31, hh = lane >> 5, i16 = lane & 15, tq = i16 >> 2, tp = i16 & 3, blk = (lane >> 4) & 1;
;     const int q0w = qb * 256 + wid * 32, nkt = 4 * qb + 4, myc = q0w >> 6;
;     bf16x8 qf[DQK / 16];
; DI void phase_attn_d(const Params& p, LAS unsigned char* lds) {
;     const bf16_t* qkv = (const bf16_t*)(p.ws + ACT); const bf16_t* lat = (const bf16_t*)(p.ws + LAT); const bf16_t* gb = (const bf16_t*)(p.ws + HBUF);
;     bf16_t* y = (bf16_t*)(p.ws + HBUF);
;     for (int pr = blockIdx.x; pr < 512; pr += gridDim.x) {
;         const int bi = pr & 255, bh = (gridDim.x == 256) ? (bi & 7) + 8 * (bi >> 6) + 32 * (pr >> 8) : pr >> 3, j = (gridDim.x == 256) ? (bi >> 3) & 7 : pr & 7, b = bh >> 4, h = bh & 15;
;         for (int half = 0; half < 2; ++half) {
;             const int qb = half ? 15 - j : j;
;             __syncthreads();
;             const int tid = otid(), wid = tid >> 6, lane = tid & 63, l32 = lane & 31;
;             const size_t tok0 = (size_t)b * SEQ, tokq = tok0 + qb * 256 + wid * 32 + l32;
;             f32x16 O[4];
;             attn_core<192, 16, 128, false, true>(lds, qkv + tokq * 7168 + h * 192, qkv + tok0 * 7168 + 3072 + h * 256, 7168, lat + tok0 * 1088 + 1024, 1088,
;                                            qkv + tok0 * 7168 + 3072 + h * 256 + 128, 7168, qb, wid, lane, p.in[27], O);
.LBB0_1556:
	s_or_b64 exec, exec, s[6:7]
	s_and_b64 vcc, exec, s[4:5]
	s_waitcnt lgkmcnt(0)
	s_barrier
	s_cbranch_vccnz .LBB0_1625
	s_load_dwordx2 s[6:7], s[0:1], 0xf0
	s_load_dwordx2 s[12:13], s[0:1], 0xd8
	v_and_b32_e32 v228, 63, v181
	v_and_b32_e32 v226, 31, v228
	v_lshrrev_b32_e32 v227, 5, v228
	v_mul_u32_u24_e32 v214, 400, v226
	v_lshl_add_u32 v214, v227, 4, v214
	v_bfe_u32 v235, v228, 2, 2
	v_lshl_add_u32 v235, v227, 2, v235
	v_mul_u32_u24_e32 v215, 320, v235
	v_and_b32_e32 v235, 3, v228
	v_lshl_add_u32 v215, v235, 3, v215
	v_bfe_u32 v235, v228, 4, 1
	v_lshl_add_u32 v215, v235, 5, v215
	v_lshrrev_b32_e32 v235, 4, v181
	v_and_b32_e32 v236, 15, v181
	v_mul_u32_u24_e32 v216, 400, v235
	v_lshl_add_u32 v216, v236, 4, v216
	v_mul_u32_u24_e32 v218, 320, v235
	v_lshl_add_u32 v218, v236, 4, v218
	v_mul_u32_u24_e32 v219, 14336, v235
	v_lshl_add_u32 v219, v236, 4, v219
	v_add_u32_e32 v220, 0x70000, v219
	v_mov_b32_e32 v222, v219
	v_mov_b32_e32 v223, v220
	v_lshrrev_b32_e32 v235, 3, v181
	v_and_b32_e32 v236, 7, v181
	v_mul_u32_u24_e32 v217, 400, v235
	v_lshl_add_u32 v217, v236, 4, v217
	v_add_u32_e32 v217, 256, v217
	v_add_u32_e32 v253, 66560, v216
	v_add_u32_e32 v254, 66560, v217
	v_add_u32_e32 v252, 66560, v214
	v_mul_u32_u24_e32 v221, 2176, v235
	v_lshl_add_u32 v221, v236, 4, v221
	v_mul_u32_u24_e32 v237, 14336, v226
	v_lshl_add_u32 v237, v227, 4, v237
	v_lshlrev_b32_e32 v238, 12, v226
	v_lshl_add_u32 v238, v227, 3, v238
	v_lshlrev_b32_e32 v239, 5, v227
	v_lshrrev_b32_e32 v235, 6, v181
	s_nop 0
	v_readfirstlane_b32 s26, v235
	s_waitcnt lgkmcnt(0)
	s_add_u32 s8, s6, 0xbf00000
	s_addc_u32 s9, s7, 0
	s_add_u32 s10, s6, 0x7f00000
	s_addc_u32 s11, s7, 0
	s_mov_b32 s14, s2

; template <int DQK, int KA8, int DV, bool BIAS, bool JOINT>
; DI void attn_core(LAS unsigned char* lds, const bf16_t* Qrow, const bf16_t* KpA, int ldkA, const bf16_t* KpB, int ldkB, const bf16_t* Vp, int ldv,
;                   int qb, int wid, int lane, const float* qng  , f32x16 (&O)[DV / 32]) {
;     ...
;     bf16x8 qf[DQK / 16];
; #pragma unroll
;     for (int s = 0; s < DQK / 16; ++s) qf[s] = *(const bf16x8*)(Qrow + 16 * s + 8 * hh);
;     if constexpr (DQK == 192) {
;         if (qng) {
;             float ssn = 0.f, ssr = 0.f;
; #pragma unroll
;             for (int s = 0; s < 12; ++s) { float f[8]; unpack8(__builtin_bit_cast(u32x4, qf[s]), f); float t = 0.f;
; #pragma unroll
;                 for (int e = 0; e < 8; ++e) t += f[e] * f[e];
;                 if (s < 8) ssn += t; else ssr += t; }
;             ssn += __shfl_xor(ssn, 32); ssr += __shfl_xor(ssr, 32);
;             const float qs = 0.07216878364870322f * LOG2E, scn = rsqrtf(ssn * (1.f / 128.f) + EPS) * qs, scr = rsqrtf(ssr * (1.f / 64.f) + EPS) * qs;
; #pragma unroll
;             for (int s = 0; s < 8; ++s) { float f[8]; unpack8(__builtin_bit_cast(u32x4, qf[s]), f);
;                 const f32x4 g0 = *(const f32x4*)(qng + 16 * s + 8 * hh), g1 = *(const f32x4*)(qng + 16 * s + 8 * hh + 4);
; #pragma unroll
;                 for (int e = 0; e < 4; ++e) { f[e] *= scn * g0[e]; f[4 + e] *= scn * g1[e]; }
;                 qf[s] = __builtin_bit_cast(bf16x8, pack8(f)); }
; DI void phase_attn_d(const Params& p, LAS unsigned char* lds) {
;     ...
;     for (int pr = blockIdx.x; pr < 512; pr += gridDim.x) {
;         const int bi = pr & 255, bh = (gridDim.x == 256) ? (bi & 7) + 8 * (bi >> 6) + 32 * (pr >> 8) : pr >> 3, j = (gridDim.x == 256) ? (bi >> 3) & 7 : pr & 7, b = bh >> 4, h = bh & 15;
;         for (int half = 0; half < 2; ++half) {
;             const int qb = half ? 15 - j : j;
;             __syncthreads();
;             const int tid = otid(), wid = tid >> 6, lane = tid & 63, l32 = lane & 31;
;             const size_t tok0 = (size_t)b * SEQ, tokq = tok0 + qb * 256 + wid * 32 + l32;
;             f32x16 O[4];
;             attn_core<192, 16, 128, false, true>(lds, qkv + tokq * 7168 + h * 192, qkv + tok0 * 7168 + 3072 + h * 256, 7168, lat + tok0 * 1088 + 1024, 1088,
;                                            qkv + tok0 * 7168 + 3072 + h * 256 + 128, 7168, qb, wid, lane, p.in[27], O);
.Lad_decoded:
	s_lshr_b32 s28, s58, 4
	s_and_b32 s27, s58, 15
	s_mov_b32 s15, 0
.Lad_half:
	s_sub_i32 s58, 15, s29
	s_cmp_eq_u32 s15, 0
	s_cselect_b32 s16, s29, s58
	s_lshl_b32 s17, s16, 2
	s_add_i32 s17, s17, 4
	s_lshl_b32 s43, s16, 8
	s_lshl_b32 s58, s26, 5
	s_add_i32 s43, s43, s58
	s_lshr_b32 s25, s43, 6
	s_lshl_b32 s58, s28, 12
	s_add_i32 s59, s58, s43
	s_mul_i32 s60, s59, 14336
	s_mul_hi_u32 s61, s59, 14336
	s_mul_i32 s42, s27, 384
	s_add_u32 s46, s8, s60
	s_addc_u32 s47, s9, s61
	s_add_u32 s46, s46, s42
	s_addc_u32 s47, s47, 0
	s_mul_i32 s60, s58, 14336
	s_mul_hi_u32 s61, s58, 14336
	s_lshl_b32 s42, s27, 9
	s_add_u32 s48, s8, s60
	s_addc_u32 s49, s9, s61
	s_add_u32 s48, s48, s42
	s_addc_u32 s49, s49, 0
	s_add_u32 s48, s48, 0x1800
	s_addc_u32 s49, s49, 0
	s_add_u32 s50, s48, 0x100
	s_addc_u32 s51, s49, 0
	s_mul_i32 s60, s58, 2176
	s_mul_hi_u32 s61, s58, 2176
	s_add_u32 s52, s6, s60
	s_addc_u32 s53, s7, s61
	s_add_u32 s52, s52, 0x800
	s_addc_u32 s53, s53, 0
	s_mov_b32 s60, s59
	s_mov_b32 s61, 0
	s_lshl_b64 s[60:61], s[60:61], 12
	s_lshl_b32 s42, s27, 8
	s_add_u32 s54, s10, s60
	s_addc_u32 s55, s11, s61
	s_add_u32 s54, s54, s42
	s_addc_u32 s55, s55, 0
	v_add_u32_e32 v229, s43, v226
	v_cvt_f32_u32_e32 v229, v229
	v_mul_f32_e32 v240, 0x3e22f983, v229
	s_barrier
	s_mov_b64 s[30:31], s[48:49]
	s_mov_b64 s[36:37], s[52:53]
	s_mov_b64 s[34:35], s[50:51]
	global_load_dwordx4 v[160:163], v219, s[30:31]
	global_load_dwordx4 v[164:167], v220, s[30:31]
	global_load_dwordx4 v[168:171], v221, s[36:37]
	global_load_dwordx4 v[112:115], v237, s[46:47] offset:0
	global_load_dwordx4 v[116:119], v237, s[46:47] offset:32
	global_load_dwordx4 v[120:123], v237, s[46:47] offset:64
	global_load_dwordx4 v[124:127], v237, s[46:47] offset:96
	global_load_dwordx4 v[128:131], v237, s[46:47] offset:128
	global_load_dwordx4 v[132:135], v237, s[46:47] offset:160
	global_load_dwordx4 v[136:139], v237, s[46:47] offset:192
	global_load_dwordx4 v[140:143], v237, s[46:47] offset:224
	global_load_dwordx4 v[144:147], v237, s[46:47] offset:256
	global_load_dwordx4 v[148:151], v237, s[46:47] offset:288
	global_load_dwordx4 v[152:155], v237, s[46:47] offset:320
	global_load_dwordx4 v[156:159], v237, s[46:47] offset:352
	s_add_u32 s30, s30, 0xe0000
	s_addc_u32 s31, s31, 0
	s_add_u32 s36, s36, 0x22000
	s_addc_u32 s37, s37, 0
	v_mov_b32_e32 v0, 0
	v_mov_b32_e32 v1, 0
	v_mov_b32_e32 v2, 0
	v_mov_b32_e32 v3, 0
	v_mov_b32_e32 v4, 0
	v_mov_b32_e32 v5, 0
	v_mov_b32_e32 v6, 0
	v_mov_b32_e32 v7, 0
	v_mov_b32_e32 v8, 0
	v_mov_b32_e32 v9, 0
	v_mov_b32_e32 v10, 0
	v_mov_b32_e32 v11, 0
	v_mov_b32_e32 v12, 0
	v_mov_b32_e32 v13, 0
	v_mov_b32_e32 v14, 0
	v_mov_b32_e32 v15, 0
	v_mov_b32_e32 v16, 0
	v_mov_b32_e32 v17, 0
	v_mov_b32_e32 v18, 0
	v_mov_b32_e32 v19, 0
	v_mov_b32_e32 v20, 0
	v_mov_b32_e32 v21, 0
	v_mov_b32_e32 v22, 0
	v_mov_b32_e32 v23, 0
	v_mov_b32_e32 v24, 0
	v_mov_b32_e32 v25, 0
	v_mov_b32_e32 v26, 0
	v_mov_b32_e32 v27, 0
	v_mov_b32_e32 v28, 0
	v_mov_b32_e32 v29, 0
	v_mov_b32_e32 v30, 0
	v_mov_b32_e32 v31, 0
	v_mov_b32_e32 v32, 0
	v_mov_b32_e32 v33, 0
	v_mov_b32_e32 v34, 0
	v_mov_b32_e32 v35, 0
	v_mov_b32_e32 v36, 0
	v_mov_b32_e32 v37, 0
	v_mov_b32_e32 v38, 0
	v_mov_b32_e32 v39, 0
	v_mov_b32_e32 v40, 0
	v_mov_b32_e32 v41, 0
	v_mov_b32_e32 v42, 0
	v_mov_b32_e32 v43, 0
	v_mov_b32_e32 v44, 0
	v_mov_b32_e32 v45, 0
	v_mov_b32_e32 v46, 0
	v_mov_b32_e32 v47, 0
	v_mov_b32_e32 v48, 0
	v_mov_b32_e32 v49, 0
	v_mov_b32_e32 v50, 0
	v_mov_b32_e32 v51, 0
	v_mov_b32_e32 v52, 0
	v_mov_b32_e32 v53, 0
	v_mov_b32_e32 v54, 0
	v_mov_b32_e32 v55, 0
	v_mov_b32_e32 v56, 0
	v_mov_b32_e32 v57, 0
	v_mov_b32_e32 v58, 0
	v_mov_b32_e32 v59, 0
	v_mov_b32_e32 v60, 0
	v_mov_b32_e32 v61, 0
	v_mov_b32_e32 v62, 0
	v_mov_b32_e32 v63, 0
	v_mov_b32_e32 v224, 0
	v_mov_b32_e32 v225, 0
	s_mov_b32 s40, 0
	s_waitcnt vmcnt(12)
	ds_write_b128 v216, v[160:163] offset:40960
	ds_write_b128 v216, v[164:167] offset:53760
	ds_write_b128 v217, v[168:171] offset:40960
	s_waitcnt lgkmcnt(0)
	global_load_dwordx4 v[160:163], v219, s[30:31]
	global_load_dwordx4 v[164:167], v220, s[30:31]
	global_load_dwordx4 v[168:171], v221, s[36:37]
	global_load_dwordx4 v[172:175], v222, s[34:35]
	global_load_dwordx4 v[176:179], v223, s[34:35]
	s_add_u32 s30, s30, 0xe0000
	s_addc_u32 s31, s31, 0
	s_add_u32 s36, s36, 0x22000
	s_addc_u32 s37, s37, 0
	s_add_u32 s34, s34, 0xe0000
	s_addc_u32 s35, s35, 0
	s_waitcnt vmcnt(5)
; template <int DQK, int KA8, int DV, bool BIAS, bool JOINT>
; DI void attn_core(LAS unsigned char* lds, const bf16_t* Qrow, const bf16_t* KpA, int ldkA, const bf16_t* KpB, int ldkB, const bf16_t* Vp, int ldv,
;                   int qb, int wid, int lane, const float* qng  , f32x16 (&O)[DV / 32]) {
;     ...
;             float ssn = 0.f, ssr = 0.f;
; #pragma unroll
;             for (int s = 0; s < 12; ++s) { float f[8]; unpack8(__builtin_bit_cast(u32x4, qf[s]), f); float t = 0.f;
; #pragma unroll
;                 for (int e = 0; e < 8; ++e) t += f[e] * f[e];
;                 if (s < 8) ssn += t; else ssr += t; }
	v_lshlrev_b32_e32 v229, 16, v112
	v_and_b32_e32 v230, 0xffff0000, v112
	v_mul_f32_e32 v232, v229, v229
	v_fmac_f32_e32 v232, v230, v230
	v_lshlrev_b32_e32 v229, 16, v113
	v_and_b32_e32 v230, 0xffff0000, v113
	v_fmac_f32_e32 v232, v229, v229
	v_fmac_f32_e32 v232, v230, v230
	v_lshlrev_b32_e32 v229, 16, v114
	v_and_b32_e32 v230, 0xffff0000, v114
	v_fmac_f32_e32 v232, v229, v229
	v_fmac_f32_e32 v232, v230, v230
	v_lshlrev_b32_e32 v229, 16, v115
	v_and_b32_e32 v230, 0xffff0000, v115
	v_fmac_f32_e32 v232, v229, v229
	v_fmac_f32_e32 v232, v230, v230
	v_lshlrev_b32_e32 v229, 16, v116
	v_and_b32_e32 v230, 0xffff0000, v116
	v_fmac_f32_e32 v232, v229, v229
	v_fmac_f32_e32 v232, v230, v230
	v_lshlrev_b32_e32 v229, 16, v117
	v_and_b32_e32 v230, 0xffff0000, v117
	v_fmac_f32_e32 v232, v229, v229
	v_fmac_f32_e32 v232, v230, v230
	v_lshlrev_b32_e32 v229, 16, v118
	v_and_b32_e32 v230, 0xffff0000, v118
	v_fmac_f32_e32 v232, v229, v229
	v_fmac_f32_e32 v232, v230, v230
	v_lshlrev_b32_e32 v229, 16, v119
	v_and_b32_e32 v230, 0xffff0000, v119
	v_fmac_f32_e32 v232, v229, v229
	v_fmac_f32_e32 v232, v230, v230
	v_lshlrev_b32_e32 v229, 16, v120
	v_and_b32_e32 v230, 0xffff0000, v120
	v_fmac_f32_e32 v232, v229, v229
	v_fmac_f32_e32 v232, v230, v230
	v_lshlrev_b32_e32 v229, 16, v121
	v_and_b32_e32 v230, 0xffff0000, v121
	v_fmac_f32_e32 v232, v229, v229
	v_fmac_f32_e32 v232, v230, v230
	v_lshlrev_b32_e32 v229, 16, v122
	v_and_b32_e32 v230, 0xffff0000, v122
	v_fmac_f32_e32 v232, v229, v229
	v_fmac_f32_e32 v232, v230, v230
	v_lshlrev_b32_e32 v229, 16, v123
	v_and_b32_e32 v230, 0xffff0000, v123
	v_fmac_f32_e32 v232, v229, v229
	v_fmac_f32_e32 v232, v230, v230
	v_lshlrev_b32_e32 v229, 16, v124
	v_and_b32_e32 v230, 0xffff0000, v124
	v_fmac_f32_e32 v232, v229, v229
	v_fmac_f32_e32 v232, v230, v230
	v_lshlrev_b32_e32 v229, 16, v125
	v_and_b32_e32 v230, 0xffff0000, v125
	v_fmac_f32_e32 v232, v229, v229
	v_fmac_f32_e32 v232, v230, v230
	v_lshlrev_b32_e32 v229, 16, v126
	v_and_b32_e32 v230, 0xffff0000, v126
	v_fmac_f32_e32 v232, v229, v229
	v_fmac_f32_e32 v232, v230, v230
	v_lshlrev_b32_e32 v229, 16, v127
	v_and_b32_e32 v230, 0xffff0000, v127
	v_fmac_f32_e32 v232, v229, v229
	v_fmac_f32_e32 v232, v230, v230
	v_lshlrev_b32_e32 v229, 16, v128
	v_and_b32_e32 v230, 0xffff0000, v128
	v_fmac_f32_e32 v232, v229, v229
	v_fmac_f32_e32 v232, v230, v230
	v_lshlrev_b32_e32 v229, 16, v129
	v_and_b32_e32 v230, 0xffff0000, v129
	v_fmac_f32_e32 v232, v229, v229
	v_fmac_f32_e32 v232, v230, v230
	v_lshlrev_b32_e32 v229, 16, v130
	v_and_b32_e32 v230, 0xffff0000, v130
	v_fmac_f32_e32 v232, v229, v229
	v_fmac_f32_e32 v232, v230, v230
	v_lshlrev_b32_e32 v229, 16, v131
	v_and_b32_e32 v230, 0xffff0000, v131
	v_fmac_f32_e32 v232, v229, v229
	v_fmac_f32_e32 v232, v230, v230
	v_lshlrev_b32_e32 v229, 16, v132
	v_and_b32_e32 v230, 0xffff0000, v132
	v_fmac_f32_e32 v232, v229, v229
	v_fmac_f32_e32 v232, v230, v230
	v_lshlrev_b32_e32 v229, 16, v133
	v_and_b32_e32 v230, 0xffff0000, v133
	v_fmac_f32_e32 v232, v229, v229
	v_fmac_f32_e32 v232, v230, v230
	v_lshlrev_b32_e32 v229, 16, v134
	v_and_b32_e32 v230, 0xffff0000, v134
	v_fmac_f32_e32 v232, v229, v229
	v_fmac_f32_e32 v232, v230, v230
	v_lshlrev_b32_e32 v229, 16, v135
	v_and_b32_e32 v230, 0xffff0000, v135
	v_fmac_f32_e32 v232, v229, v229
	v_fmac_f32_e32 v232, v230, v230
	v_lshlrev_b32_e32 v229, 16, v136
	v_and_b32_e32 v230, 0xffff0000, v136
	v_fmac_f32_e32 v232, v229, v229
	v_fmac_f32_e32 v232, v230, v230
	v_lshlrev_b32_e32 v229, 16, v137
	v_and_b32_e32 v230, 0xffff0000, v137
	v_fmac_f32_e32 v232, v229, v229
	v_fmac_f32_e32 v232, v230, v230
	v_lshlrev_b32_e32 v229, 16, v138
	v_and_b32_e32 v230, 0xffff0000, v138
	v_fmac_f32_e32 v232, v229, v229
	v_fmac_f32_e32 v232, v230, v230
	v_lshlrev_b32_e32 v229, 16, v139
	v_and_b32_e32 v230, 0xffff0000, v139
	v_fmac_f32_e32 v232, v229, v229
	v_fmac_f32_e32 v232, v230, v230
	v_lshlrev_b32_e32 v229, 16, v140
	v_and_b32_e32 v230, 0xffff0000, v140
	v_fmac_f32_e32 v232, v229, v229
	v_fmac_f32_e32 v232, v230, v230
	v_lshlrev_b32_e32 v229, 16, v141
	v_and_b32_e32 v230, 0xffff0000, v141
	v_fmac_f32_e32 v232, v229, v229
	v_fmac_f32_e32 v232, v230, v230
	v_lshlrev_b32_e32 v229, 16, v142
	v_and_b32_e32 v230, 0xffff0000, v142
	v_fmac_f32_e32 v232, v229, v229
	v_fmac_f32_e32 v232, v230, v230
	v_lshlrev_b32_e32 v229, 16, v143
	v_and_b32_e32 v230, 0xffff0000, v143
	v_fmac_f32_e32 v232, v229, v229
	v_fmac_f32_e32 v232, v230, v230
	v_lshlrev_b32_e32 v229, 16, v144
	v_and_b32_e32 v230, 0xffff0000, v144
	v_mul_f32_e32 v233, v229, v229
	v_fmac_f32_e32 v233, v230, v230
	v_lshlrev_b32_e32 v229, 16, v145
	v_and_b32_e32 v230, 0xffff0000, v145
	v_fmac_f32_e32 v233, v229, v229
	v_fmac_f32_e32 v233, v230, v230
	v_lshlrev_b32_e32 v229, 16, v146
	v_and_b32_e32 v230, 0xffff0000, v146
	v_fmac_f32_e32 v233, v229, v229
	v_fmac_f32_e32 v233, v230, v230
	v_lshlrev_b32_e32 v229, 16, v147
	v_and_b32_e32 v230, 0xffff0000, v147
	v_fmac_f32_e32 v233, v229, v229
	v_fmac_f32_e32 v233, v230, v230
	v_lshlrev_b32_e32 v229, 16, v148
	v_and_b32_e32 v230, 0xffff0000, v148
	v_fmac_f32_e32 v233, v229, v229
	v_fmac_f32_e32 v233, v230, v230
	v_lshlrev_b32_e32 v229, 16, v149
	v_and_b32_e32 v230, 0xffff0000, v149
	v_fmac_f32_e32 v233, v229, v229
	v_fmac_f32_e32 v233, v230, v230
	v_lshlrev_b32_e32 v229, 16, v150
	v_and_b32_e32 v230, 0xffff0000, v150
	v_fmac_f32_e32 v233, v229, v229
	v_fmac_f32_e32 v233, v230, v230
	v_lshlrev_b32_e32 v229, 16, v151
	v_and_b32_e32 v230, 0xffff0000, v151
	v_fmac_f32_e32 v233, v229, v229
	v_fmac_f32_e32 v233, v230, v230
	v_lshlrev_b32_e32 v229, 16, v152
	v_and_b32_e32 v230, 0xffff0000, v152
	v_fmac_f32_e32 v233, v229, v229
	v_fmac_f32_e32 v233, v230, v230
; DI u32x4 pack8(const float (&f)[8]) { u32x4 w; w.x = pk2(f[0], f[1]); w.y = pk2(f[2], f[3]); w.z = pk2(f[4], f[5]); w.w = pk2(f[6], f[7]); return w; }
; template <int DQK, int KA8, int DV, bool BIAS, bool JOINT>
; DI void attn_core(LAS unsigned char* lds, const bf16_t* Qrow, const bf16_t* KpA, int ldkA, const bf16_t* KpB, int ldkB, const bf16_t* Vp, int ldv,
;                   int qb, int wid, int lane, const float* qng  , f32x16 (&O)[DV / 32]) {
;     ...
;                 if (s < 8) ssn += t; else ssr += t; }
;             ssn += __shfl_xor(ssn, 32); ssr += __shfl_xor(ssr, 32);
;             const float qs = 0.07216878364870322f * LOG2E, scn = rsqrtf(ssn * (1.f / 128.f) + EPS) * qs, scr = rsqrtf(ssr * (1.f / 64.f) + EPS) * qs;
; #pragma unroll
;             for (int s = 0; s < 8; ++s) { float f[8]; unpack8(__builtin_bit_cast(u32x4, qf[s]), f);
;                 const f32x4 g0 = *(const f32x4*)(qng + 16 * s + 8 * hh), g1 = *(const f32x4*)(qng + 16 * s + 8 * hh + 4);
; #pragma unroll
;                 for (int e = 0; e < 4; ++e) { f[e] *= scn * g0[e]; f[4 + e] *= scn * g1[e]; }
;                 qf[s] = __builtin_bit_cast(bf16x8, pack8(f)); }
	v_lshlrev_b32_e32 v229, 16, v153
	v_and_b32_e32 v230, 0xffff0000, v153
	v_fmac_f32_e32 v233, v229, v229
	v_fmac_f32_e32 v233, v230, v230
	v_lshlrev_b32_e32 v229, 16, v154
	v_and_b32_e32 v230, 0xffff0000, v154
	v_fmac_f32_e32 v233, v229, v229
	v_fmac_f32_e32 v233, v230, v230
	v_lshlrev_b32_e32 v229, 16, v155
	v_and_b32_e32 v230, 0xffff0000, v155
	v_fmac_f32_e32 v233, v229, v229
	v_fmac_f32_e32 v233, v230, v230
	v_lshlrev_b32_e32 v229, 16, v156
	v_and_b32_e32 v230, 0xffff0000, v156
	v_fmac_f32_e32 v233, v229, v229
	v_fmac_f32_e32 v233, v230, v230
	v_lshlrev_b32_e32 v229, 16, v157
	v_and_b32_e32 v230, 0xffff0000, v157
	v_fmac_f32_e32 v233, v229, v229
	v_fmac_f32_e32 v233, v230, v230
	v_lshlrev_b32_e32 v229, 16, v158
	v_and_b32_e32 v230, 0xffff0000, v158
	v_fmac_f32_e32 v233, v229, v229
	v_fmac_f32_e32 v233, v230, v230
	v_lshlrev_b32_e32 v229, 16, v159
	v_and_b32_e32 v230, 0xffff0000, v159
	v_fmac_f32_e32 v233, v229, v229
	v_fmac_f32_e32 v233, v230, v230
	v_mov_b32_e32 v230, v232
	v_mov_b32_e32 v231, v232
	s_nop 1
	v_permlane32_swap_b32_e32 v230, v231
	s_nop 1
	v_add_f32_e32 v232, v230, v231
	v_mov_b32_e32 v230, v233
	v_mov_b32_e32 v231, v233
	s_nop 1
	v_permlane32_swap_b32_e32 v230, v231
	s_nop 1
	v_add_f32_e32 v233, v230, v231
	v_mul_f32_e32 v232, 0x3c000000, v232
	v_mul_f32_e32 v233, 0x3c800000, v233
	v_add_f32_e32 v232, 0x358637bd, v232
	v_add_f32_e32 v233, 0x358637bd, v233
	v_rsq_f32_e32 v232, v232
	v_rsq_f32_e32 v233, v233
	s_nop 1
	v_mul_f32_e32 v241, 0x3dd53b95, v232
	v_mul_f32_e32 v242, 0x3dd53b95, v233
	global_load_dwordx4 v[182:185], v239, s[12:13] offset:0
	global_load_dwordx4 v[186:189], v239, s[12:13] offset:16
	s_waitcnt vmcnt(0)
	v_lshlrev_b32_e32 v229, 16, v112
	v_and_b32_e32 v230, 0xffff0000, v112
	v_mul_f32_e32 v234, v241, v182
	v_mul_f32_e32 v235, v241, v183
	v_mul_f32_e32 v229, v229, v234
	v_mul_f32_e32 v230, v230, v235
	v_cvt_pk_bf16_f32 v112, v229, v230
	v_lshlrev_b32_e32 v229, 16, v113
	v_and_b32_e32 v230, 0xffff0000, v113
	v_mul_f32_e32 v234, v241, v184
	v_mul_f32_e32 v235, v241, v185
	v_mul_f32_e32 v229, v229, v234
	v_mul_f32_e32 v230, v230, v235
	v_cvt_pk_bf16_f32 v113, v229, v230
	v_lshlrev_b32_e32 v229, 16, v114
	v_and_b32_e32 v230, 0xffff0000, v114
	v_mul_f32_e32 v234, v241, v186
	v_mul_f32_e32 v235, v241, v187
	v_mul_f32_e32 v229, v229, v234
	v_mul_f32_e32 v230, v230, v235
	v_cvt_pk_bf16_f32 v114, v229, v230
	v_lshlrev_b32_e32 v229, 16, v115
	v_and_b32_e32 v230, 0xffff0000, v115
	v_mul_f32_e32 v234, v241, v188
	v_mul_f32_e32 v235, v241, v189
	v_mul_f32_e32 v229, v229, v234
	v_mul_f32_e32 v230, v230, v235
	v_cvt_pk_bf16_f32 v115, v229, v230
	global_load_dwordx4 v[182:185], v239, s[12:13] offset:64
	global_load_dwordx4 v[186:189], v239, s[12:13] offset:80
	s_waitcnt vmcnt(0)
	v_lshlrev_b32_e32 v229, 16, v116
	v_and_b32_e32 v230, 0xffff0000, v116
	v_mul_f32_e32 v234, v241, v182
	v_mul_f32_e32 v235, v241, v183
	v_mul_f32_e32 v229, v229, v234
	v_mul_f32_e32 v230, v230, v235
	v_cvt_pk_bf16_f32 v116, v229, v230
	v_lshlrev_b32_e32 v229, 16, v117
	v_and_b32_e32 v230, 0xffff0000, v117
	v_mul_f32_e32 v234, v241, v184
	v_mul_f32_e32 v235, v241, v185
	v_mul_f32_e32 v229, v229, v234
	v_mul_f32_e32 v230, v230, v235
	v_cvt_pk_bf16_f32 v117, v229, v230
	v_lshlrev_b32_e32 v229, 16, v118
	v_and_b32_e32 v230, 0xffff0000, v118
	v_mul_f32_e32 v234, v241, v186
	v_mul_f32_e32 v235, v241, v187
	v_mul_f32_e32 v229, v229, v234
	v_mul_f32_e32 v230, v230, v235
	v_cvt_pk_bf16_f32 v118, v229, v230
	v_lshlrev_b32_e32 v229, 16, v119
	v_and_b32_e32 v230, 0xffff0000, v119
	v_mul_f32_e32 v234, v241, v188
	v_mul_f32_e32 v235, v241, v189
	v_mul_f32_e32 v229, v229, v234
	v_mul_f32_e32 v230, v230, v235
	v_cvt_pk_bf16_f32 v119, v229, v230
	global_load_dwordx4 v[182:185], v239, s[12:13] offset:128
	global_load_dwordx4 v[186:189], v239, s[12:13] offset:144
	s_waitcnt vmcnt(0)
	v_lshlrev_b32_e32 v229, 16, v120
	v_and_b32_e32 v230, 0xffff0000, v120
	v_mul_f32_e32 v234, v241, v182
	v_mul_f32_e32 v235, v241, v183
	v_mul_f32_e32 v229, v229, v234
	v_mul_f32_e32 v230, v230, v235
	v_cvt_pk_bf16_f32 v120, v229, v230
	v_lshlrev_b32_e32 v229, 16, v121
	v_and_b32_e32 v230, 0xffff0000, v121
	v_mul_f32_e32 v234, v241, v184
	v_mul_f32_e32 v235, v241, v185
	v_mul_f32_e32 v229, v229, v234
	v_mul_f32_e32 v230, v230, v235
	v_cvt_pk_bf16_f32 v121, v229, v230
	v_lshlrev_b32_e32 v229, 16, v122
	v_and_b32_e32 v230, 0xffff0000, v122
	v_mul_f32_e32 v234, v241, v186
	v_mul_f32_e32 v235, v241, v187
	v_mul_f32_e32 v229, v229, v234
	v_mul_f32_e32 v230, v230, v235
	v_cvt_pk_bf16_f32 v122, v229, v230
	v_lshlrev_b32_e32 v229, 16, v123
	v_and_b32_e32 v230, 0xffff0000, v123
	v_mul_f32_e32 v234, v241, v188
	v_mul_f32_e32 v235, v241, v189
	v_mul_f32_e32 v229, v229, v234
	v_mul_f32_e32 v230, v230, v235
	v_cvt_pk_bf16_f32 v123, v229, v230
	global_load_dwordx4 v[182:185], v239, s[12:13] offset:192
	global_load_dwordx4 v[186:189], v239, s[12:13] offset:208
	s_waitcnt vmcnt(0)
	v_lshlrev_b32_e32 v229, 16, v124
	v_and_b32_e32 v230, 0xffff0000, v124
	v_mul_f32_e32 v234, v241, v182
	v_mul_f32_e32 v235, v241, v183
	v_mul_f32_e32 v229, v229, v234
	v_mul_f32_e32 v230, v230, v235
	v_cvt_pk_bf16_f32 v124, v229, v230
	v_lshlrev_b32_e32 v229, 16, v125
	v_and_b32_e32 v230, 0xffff0000, v125
	v_mul_f32_e32 v234, v241, v184
	v_mul_f32_e32 v235, v241, v185
	v_mul_f32_e32 v229, v229, v234
	v_mul_f32_e32 v230, v230, v235
	v_cvt_pk_bf16_f32 v125, v229, v230
	v_lshlrev_b32_e32 v229, 16, v126
	v_and_b32_e32 v230, 0xffff0000, v126
	v_mul_f32_e32 v234, v241, v186
	v_mul_f32_e32 v235, v241, v187
	v_mul_f32_e32 v229, v229, v234
	v_mul_f32_e32 v230, v230, v235
	v_cvt_pk_bf16_f32 v126, v229, v230
	v_lshlrev_b32_e32 v229, 16, v127
	v_and_b32_e32 v230, 0xffff0000, v127
	v_mul_f32_e32 v234, v241, v188
	v_mul_f32_e32 v235, v241, v189
	v_mul_f32_e32 v229, v229, v234
	v_mul_f32_e32 v230, v230, v235
	v_cvt_pk_bf16_f32 v127, v229, v230
	global_load_dwordx4 v[182:185], v239, s[12:13] offset:256
	global_load_dwordx4 v[186:189], v239, s[12:13] offset:272
	s_waitcnt vmcnt(0)
; DI u32x4 pack8(const float (&f)[8]) { u32x4 w; w.x = pk2(f[0], f[1]); w.y = pk2(f[2], f[3]); w.z = pk2(f[4], f[5]); w.w = pk2(f[6], f[7]); return w; }
; template <int DQK, int KA8, int DV, bool BIAS, bool JOINT>
; DI void attn_core(LAS unsigned char* lds, const bf16_t* Qrow, const bf16_t* KpA, int ldkA, const bf16_t* KpB, int ldkB, const bf16_t* Vp, int ldv,
;                   int qb, int wid, int lane, const float* qng  , f32x16 (&O)[DV / 32]) {
;     ...
;             for (int s = 0; s < 8; ++s) { float f[8]; unpack8(__builtin_bit_cast(u32x4, qf[s]), f);
;                 const f32x4 g0 = *(const f32x4*)(qng + 16 * s + 8 * hh), g1 = *(const f32x4*)(qng + 16 * s + 8 * hh + 4);
; #pragma unroll
;                 for (int e = 0; e < 4; ++e) { f[e] *= scn * g0[e]; f[4 + e] *= scn * g1[e]; }
;                 qf[s] = __builtin_bit_cast(bf16x8, pack8(f)); }
;             const float posr = (float)(qb * 256 + wid * 32 + l32) * 0.15915494309189535f;
; #pragma unroll
;             for (int s = 8; s < 10; ++s) { float f1[8], f2[8]; unpack8(__builtin_bit_cast(u32x4, qf[s]), f1); unpack8(__builtin_bit_cast(u32x4, qf[s + 2]), f2);
; #pragma unroll
;                 for (int e = 0; e < 8; ++e) { const int i = 16 * (s - 8) + 8 * hh + e;
;                     const float a1 = f1[e] * scr * qng[128 + i], a2 = f2[e] * scr * qng[160 + i];
	v_lshlrev_b32_e32 v229, 16, v128
	v_and_b32_e32 v230, 0xffff0000, v128
	v_mul_f32_e32 v234, v241, v182
	v_mul_f32_e32 v235, v241, v183
	v_mul_f32_e32 v229, v229, v234
	v_mul_f32_e32 v230, v230, v235
	v_cvt_pk_bf16_f32 v128, v229, v230
	v_lshlrev_b32_e32 v229, 16, v129
	v_and_b32_e32 v230, 0xffff0000, v129
	v_mul_f32_e32 v234, v241, v184
	v_mul_f32_e32 v235, v241, v185
	v_mul_f32_e32 v229, v229, v234
	v_mul_f32_e32 v230, v230, v235
	v_cvt_pk_bf16_f32 v129, v229, v230
	v_lshlrev_b32_e32 v229, 16, v130
	v_and_b32_e32 v230, 0xffff0000, v130
	v_mul_f32_e32 v234, v241, v186
	v_mul_f32_e32 v235, v241, v187
	v_mul_f32_e32 v229, v229, v234
	v_mul_f32_e32 v230, v230, v235
	v_cvt_pk_bf16_f32 v130, v229, v230
	v_lshlrev_b32_e32 v229, 16, v131
	v_and_b32_e32 v230, 0xffff0000, v131
	v_mul_f32_e32 v234, v241, v188
	v_mul_f32_e32 v235, v241, v189
	v_mul_f32_e32 v229, v229, v234
	v_mul_f32_e32 v230, v230, v235
	v_cvt_pk_bf16_f32 v131, v229, v230
	global_load_dwordx4 v[182:185], v239, s[12:13] offset:320
	global_load_dwordx4 v[186:189], v239, s[12:13] offset:336
	s_waitcnt vmcnt(0)
	v_lshlrev_b32_e32 v229, 16, v132
	v_and_b32_e32 v230, 0xffff0000, v132
	v_mul_f32_e32 v234, v241, v182
	v_mul_f32_e32 v235, v241, v183
	v_mul_f32_e32 v229, v229, v234
	v_mul_f32_e32 v230, v230, v235
	v_cvt_pk_bf16_f32 v132, v229, v230
	v_lshlrev_b32_e32 v229, 16, v133
	v_and_b32_e32 v230, 0xffff0000, v133
	v_mul_f32_e32 v234, v241, v184
	v_mul_f32_e32 v235, v241, v185
	v_mul_f32_e32 v229, v229, v234
	v_mul_f32_e32 v230, v230, v235
	v_cvt_pk_bf16_f32 v133, v229, v230
	v_lshlrev_b32_e32 v229, 16, v134
	v_and_b32_e32 v230, 0xffff0000, v134
	v_mul_f32_e32 v234, v241, v186
	v_mul_f32_e32 v235, v241, v187
	v_mul_f32_e32 v229, v229, v234
	v_mul_f32_e32 v230, v230, v235
	v_cvt_pk_bf16_f32 v134, v229, v230
	v_lshlrev_b32_e32 v229, 16, v135
	v_and_b32_e32 v230, 0xffff0000, v135
	v_mul_f32_e32 v234, v241, v188
	v_mul_f32_e32 v235, v241, v189
	v_mul_f32_e32 v229, v229, v234
	v_mul_f32_e32 v230, v230, v235
	v_cvt_pk_bf16_f32 v135, v229, v230
	global_load_dwordx4 v[182:185], v239, s[12:13] offset:384
	global_load_dwordx4 v[186:189], v239, s[12:13] offset:400
	s_waitcnt vmcnt(0)
	v_lshlrev_b32_e32 v229, 16, v136
	v_and_b32_e32 v230, 0xffff0000, v136
	v_mul_f32_e32 v234, v241, v182
	v_mul_f32_e32 v235, v241, v183
	v_mul_f32_e32 v229, v229, v234
	v_mul_f32_e32 v230, v230, v235
	v_cvt_pk_bf16_f32 v136, v229, v230
	v_lshlrev_b32_e32 v229, 16, v137
	v_and_b32_e32 v230, 0xffff0000, v137
	v_mul_f32_e32 v234, v241, v184
	v_mul_f32_e32 v235, v241, v185
	v_mul_f32_e32 v229, v229, v234
	v_mul_f32_e32 v230, v230, v235
	v_cvt_pk_bf16_f32 v137, v229, v230
	v_lshlrev_b32_e32 v229, 16, v138
	v_and_b32_e32 v230, 0xffff0000, v138
	v_mul_f32_e32 v234, v241, v186
	v_mul_f32_e32 v235, v241, v187
	v_mul_f32_e32 v229, v229, v234
	v_mul_f32_e32 v230, v230, v235
	v_cvt_pk_bf16_f32 v138, v229, v230
	v_lshlrev_b32_e32 v229, 16, v139
	v_and_b32_e32 v230, 0xffff0000, v139
	v_mul_f32_e32 v234, v241, v188
	v_mul_f32_e32 v235, v241, v189
	v_mul_f32_e32 v229, v229, v234
	v_mul_f32_e32 v230, v230, v235
	v_cvt_pk_bf16_f32 v139, v229, v230
	global_load_dwordx4 v[182:185], v239, s[12:13] offset:448
	global_load_dwordx4 v[186:189], v239, s[12:13] offset:464
	s_waitcnt vmcnt(0)
	v_lshlrev_b32_e32 v229, 16, v140
	v_and_b32_e32 v230, 0xffff0000, v140
	v_mul_f32_e32 v234, v241, v182
	v_mul_f32_e32 v235, v241, v183
	v_mul_f32_e32 v229, v229, v234
	v_mul_f32_e32 v230, v230, v235
	v_cvt_pk_bf16_f32 v140, v229, v230
	v_lshlrev_b32_e32 v229, 16, v141
	v_and_b32_e32 v230, 0xffff0000, v141
	v_mul_f32_e32 v234, v241, v184
	v_mul_f32_e32 v235, v241, v185
	v_mul_f32_e32 v229, v229, v234
	v_mul_f32_e32 v230, v230, v235
	v_cvt_pk_bf16_f32 v141, v229, v230
	v_lshlrev_b32_e32 v229, 16, v142
	v_and_b32_e32 v230, 0xffff0000, v142
	v_mul_f32_e32 v234, v241, v186
	v_mul_f32_e32 v235, v241, v187
	v_mul_f32_e32 v229, v229, v234
	v_mul_f32_e32 v230, v230, v235
	v_cvt_pk_bf16_f32 v142, v229, v230
	v_lshlrev_b32_e32 v229, 16, v143
	v_and_b32_e32 v230, 0xffff0000, v143
	v_mul_f32_e32 v234, v241, v188
	v_mul_f32_e32 v235, v241, v189
	v_mul_f32_e32 v229, v229, v234
	v_mul_f32_e32 v230, v230, v235
	v_cvt_pk_bf16_f32 v143, v229, v230
	global_load_dwordx4 v[182:185], v239, s[12:13] offset:512
	global_load_dwordx4 v[186:189], v239, s[12:13] offset:528
	global_load_dwordx4 v[190:193], v239, s[12:13] offset:640
	global_load_dwordx4 v[194:197], v239, s[12:13] offset:656
	s_waitcnt vmcnt(0)
; DI u32x4 pack8(const float (&f)[8]) { u32x4 w; w.x = pk2(f[0], f[1]); w.y = pk2(f[2], f[3]); w.z = pk2(f[4], f[5]); w.w = pk2(f[6], f[7]); return w; }
; template <int DQK, int KA8, int DV, bool BIAS, bool JOINT>
; DI void attn_core(LAS unsigned char* lds, const bf16_t* Qrow, const bf16_t* KpA, int ldkA, const bf16_t* KpB, int ldkB, const bf16_t* Vp, int ldv,
;                   int qb, int wid, int lane, const float* qng  , f32x16 (&O)[DV / 32]) {
;     ...
;             const float posr = (float)(qb * 256 + wid * 32 + l32) * 0.15915494309189535f;
; #pragma unroll
;             for (int s = 8; s < 10; ++s) { float f1[8], f2[8]; unpack8(__builtin_bit_cast(u32x4, qf[s]), f1); unpack8(__builtin_bit_cast(u32x4, qf[s + 2]), f2);
; #pragma unroll
;                 for (int e = 0; e < 8; ++e) { const int i = 16 * (s - 8) + 8 * hh + e;
;                     const float a1 = f1[e] * scr * qng[128 + i], a2 = f2[e] * scr * qng[160 + i];
;                     float rev = posr * __builtin_amdgcn_exp2f(-(float)i * 0.41524101186092029f); rev -= floorf(rev);
;                     const float sn = __builtin_amdgcn_sinf(rev), cs = __builtin_amdgcn_cosf(rev);
;                     f1[e] = a1 * cs - a2 * sn; f2[e] = a2 * cs + a1 * sn; }
;                 qf[s] = __builtin_bit_cast(bf16x8, pack8(f1)); qf[s + 2] = __builtin_bit_cast(bf16x8, pack8(f2)); }
	v_lshl_add_u32 v229, v227, 3, 0
	v_cvt_f32_u32_e32 v229, v229
	v_mul_f32_e32 v229, 0xbed49a78, v229
	v_exp_f32_e32 v229, v229
	v_lshlrev_b32_e32 v234, 16, v144
	v_lshlrev_b32_e32 v235, 16, v152
	v_mul_f32_e32 v229, v240, v229
	v_mul_f32_e32 v234, v234, v242
	v_mul_f32_e32 v235, v235, v242
	v_fract_f32_e32 v229, v229
	v_mul_f32_e32 v234, v234, v182
	v_mul_f32_e32 v235, v235, v190
	v_sin_f32_e32 v230, v229
	v_cos_f32_e32 v231, v229
	s_nop 1
	v_mul_f32_e32 v236, v235, v230
	v_mul_f32_e32 v233, v234, v230
	v_fma_f32 v243, v234, v231, -v236
	v_fma_f32 v245, v235, v231, v233
	v_lshl_add_u32 v229, v227, 3, 1
	v_cvt_f32_u32_e32 v229, v229
	v_mul_f32_e32 v229, 0xbed49a78, v229
	v_exp_f32_e32 v229, v229
	v_and_b32_e32 v234, 0xffff0000, v144
	v_and_b32_e32 v235, 0xffff0000, v152
	v_mul_f32_e32 v229, v240, v229
	v_mul_f32_e32 v234, v234, v242
	v_mul_f32_e32 v235, v235, v242
	v_fract_f32_e32 v229, v229
	v_mul_f32_e32 v234, v234, v183
	v_mul_f32_e32 v235, v235, v191
	v_sin_f32_e32 v230, v229
	v_cos_f32_e32 v231, v229
	s_nop 1
	v_mul_f32_e32 v236, v235, v230
	v_mul_f32_e32 v233, v234, v230
	v_fma_f32 v244, v234, v231, -v236
	v_fma_f32 v246, v235, v231, v233
	v_cvt_pk_bf16_f32 v144, v243, v244
	v_cvt_pk_bf16_f32 v152, v245, v246
	v_lshl_add_u32 v229, v227, 3, 2
	v_cvt_f32_u32_e32 v229, v229
	v_mul_f32_e32 v229, 0xbed49a78, v229
	v_exp_f32_e32 v229, v229
	v_lshlrev_b32_e32 v234, 16, v145
	v_lshlrev_b32_e32 v235, 16, v153
	v_mul_f32_e32 v229, v240, v229
	v_mul_f32_e32 v234, v234, v242
	v_mul_f32_e32 v235, v235, v242
	v_fract_f32_e32 v229, v229
	v_mul_f32_e32 v234, v234, v184
	v_mul_f32_e32 v235, v235, v192
	v_sin_f32_e32 v230, v229
	v_cos_f32_e32 v231, v229
	s_nop 1
	v_mul_f32_e32 v236, v235, v230
	v_mul_f32_e32 v233, v234, v230
	v_fma_f32 v243, v234, v231, -v236
	v_fma_f32 v245, v235, v231, v233
	v_lshl_add_u32 v229, v227, 3, 3
	v_cvt_f32_u32_e32 v229, v229
	v_mul_f32_e32 v229, 0xbed49a78, v229
	v_exp_f32_e32 v229, v229
	v_and_b32_e32 v234, 0xffff0000, v145
	v_and_b32_e32 v235, 0xffff0000, v153
	v_mul_f32_e32 v229, v240, v229
	v_mul_f32_e32 v234, v234, v242
	v_mul_f32_e32 v235, v235, v242
	v_fract_f32_e32 v229, v229
	v_mul_f32_e32 v234, v234, v185
	v_mul_f32_e32 v235, v235, v193
	v_sin_f32_e32 v230, v229
	v_cos_f32_e32 v231, v229
	s_nop 1
	v_mul_f32_e32 v236, v235, v230
	v_mul_f32_e32 v233, v234, v230
	v_fma_f32 v244, v234, v231, -v236
	v_fma_f32 v246, v235, v231, v233
	v_cvt_pk_bf16_f32 v145, v243, v244
	v_cvt_pk_bf16_f32 v153, v245, v246
	v_lshl_add_u32 v229, v227, 3, 4
	v_cvt_f32_u32_e32 v229, v229
	v_mul_f32_e32 v229, 0xbed49a78, v229
	v_exp_f32_e32 v229, v229
	v_lshlrev_b32_e32 v234, 16, v146
	v_lshlrev_b32_e32 v235, 16, v154
	v_mul_f32_e32 v229, v240, v229
	v_mul_f32_e32 v234, v234, v242
	v_mul_f32_e32 v235, v235, v242
	v_fract_f32_e32 v229, v229
	v_mul_f32_e32 v234, v234, v186
	v_mul_f32_e32 v235, v235, v194
	v_sin_f32_e32 v230, v229
	v_cos_f32_e32 v231, v229
	s_nop 1
	v_mul_f32_e32 v236, v235, v230
	v_mul_f32_e32 v233, v234, v230
	v_fma_f32 v243, v234, v231, -v236
	v_fma_f32 v245, v235, v231, v233
	v_lshl_add_u32 v229, v227, 3, 5
	v_cvt_f32_u32_e32 v229, v229
	v_mul_f32_e32 v229, 0xbed49a78, v229
	v_exp_f32_e32 v229, v229
	v_and_b32_e32 v234, 0xffff0000, v146
	v_and_b32_e32 v235, 0xffff0000, v154
	v_mul_f32_e32 v229, v240, v229
	v_mul_f32_e32 v234, v234, v242
	v_mul_f32_e32 v235, v235, v242
	v_fract_f32_e32 v229, v229
	v_mul_f32_e32 v234, v234, v187
	v_mul_f32_e32 v235, v235, v195
	v_sin_f32_e32 v230, v229
	v_cos_f32_e32 v231, v229
	s_nop 1
	v_mul_f32_e32 v236, v235, v230
	v_mul_f32_e32 v233, v234, v230
	v_fma_f32 v244, v234, v231, -v236
	v_fma_f32 v246, v235, v231, v233
	v_cvt_pk_bf16_f32 v146, v243, v244
	v_cvt_pk_bf16_f32 v154, v245, v246
	v_lshl_add_u32 v229, v227, 3, 6
	v_cvt_f32_u32_e32 v229, v229
	v_mul_f32_e32 v229, 0xbed49a78, v229
	v_exp_f32_e32 v229, v229
	v_lshlrev_b32_e32 v234, 16, v147
	v_lshlrev_b32_e32 v235, 16, v155
	v_mul_f32_e32 v229, v240, v229
	v_mul_f32_e32 v234, v234, v242
	v_mul_f32_e32 v235, v235, v242
	v_fract_f32_e32 v229, v229
	v_mul_f32_e32 v234, v234, v188
	v_mul_f32_e32 v235, v235, v196
	v_sin_f32_e32 v230, v229
	v_cos_f32_e32 v231, v229
	s_nop 1
	v_mul_f32_e32 v236, v235, v230
	v_mul_f32_e32 v233, v234, v230
	v_fma_f32 v243, v234, v231, -v236
	v_fma_f32 v245, v235, v231, v233
	v_lshl_add_u32 v229, v227, 3, 7
	v_cvt_f32_u32_e32 v229, v229
	v_mul_f32_e32 v229, 0xbed49a78, v229
	v_exp_f32_e32 v229, v229
	v_and_b32_e32 v234, 0xffff0000, v147
	v_and_b32_e32 v235, 0xffff0000, v155
	v_mul_f32_e32 v229, v240, v229
	v_mul_f32_e32 v234, v234, v242
	v_mul_f32_e32 v235, v235, v242
	v_fract_f32_e32 v229, v229
	v_mul_f32_e32 v234, v234, v189
	v_mul_f32_e32 v235, v235, v197
	v_sin_f32_e32 v230, v229
	v_cos_f32_e32 v231, v229
	s_nop 1
	v_mul_f32_e32 v236, v235, v230
	v_mul_f32_e32 v233, v234, v230
	v_fma_f32 v244, v234, v231, -v236
	v_fma_f32 v246, v235, v231, v233
	v_cvt_pk_bf16_f32 v147, v243, v244
	v_cvt_pk_bf16_f32 v155, v245, v246
	global_load_dwordx4 v[182:185], v239, s[12:13] offset:576
	global_load_dwordx4 v[186:189], v239, s[12:13] offset:592
	global_load_dwordx4 v[190:193], v239, s[12:13] offset:704
	global_load_dwordx4 v[194:197], v239, s[12:13] offset:720
	s_waitcnt vmcnt(0)
; DI u32x4 pack8(const float (&f)[8]) { u32x4 w; w.x = pk2(f[0], f[1]); w.y = pk2(f[2], f[3]); w.z = pk2(f[4], f[5]); w.w = pk2(f[6], f[7]); return w; }
; template <int DQK, int KA8, int DV, bool BIAS, bool JOINT>
; DI void attn_core(LAS unsigned char* lds, const bf16_t* Qrow, const bf16_t* KpA, int ldkA, const bf16_t* KpB, int ldkB, const bf16_t* Vp, int ldv,
;                   int qb, int wid, int lane, const float* qng  , f32x16 (&O)[DV / 32]) {
;     ...
; #pragma unroll
;             for (int s = 8; s < 10; ++s) { float f1[8], f2[8]; unpack8(__builtin_bit_cast(u32x4, qf[s]), f1); unpack8(__builtin_bit_cast(u32x4, qf[s + 2]), f2);
; #pragma unroll
;                 for (int e = 0; e < 8; ++e) { const int i = 16 * (s - 8) + 8 * hh + e;
;                     const float a1 = f1[e] * scr * qng[128 + i], a2 = f2[e] * scr * qng[160 + i];
;                     float rev = posr * __builtin_amdgcn_exp2f(-(float)i * 0.41524101186092029f); rev -= floorf(rev);
;                     const float sn = __builtin_amdgcn_sinf(rev), cs = __builtin_amdgcn_cosf(rev);
;                     f1[e] = a1 * cs - a2 * sn; f2[e] = a2 * cs + a1 * sn; }
;                 qf[s] = __builtin_bit_cast(bf16x8, pack8(f1)); qf[s + 2] = __builtin_bit_cast(bf16x8, pack8(f2)); }
;             __builtin_amdgcn_sched_barrier(0);
;     ...
;     gload(0); lstore(0); __syncthreads();
;     for (int kt = 0; kt < nkt; ++kt) {
	v_lshl_add_u32 v229, v227, 3, 16
	v_cvt_f32_u32_e32 v229, v229
	v_mul_f32_e32 v229, 0xbed49a78, v229
	v_exp_f32_e32 v229, v229
	v_lshlrev_b32_e32 v234, 16, v148
	v_lshlrev_b32_e32 v235, 16, v156
	v_mul_f32_e32 v229, v240, v229
	v_mul_f32_e32 v234, v234, v242
	v_mul_f32_e32 v235, v235, v242
	v_fract_f32_e32 v229, v229
	v_mul_f32_e32 v234, v234, v182
	v_mul_f32_e32 v235, v235, v190
	v_sin_f32_e32 v230, v229
	v_cos_f32_e32 v231, v229
	s_nop 1
	v_mul_f32_e32 v236, v235, v230
	v_mul_f32_e32 v233, v234, v230
	v_fma_f32 v243, v234, v231, -v236
	v_fma_f32 v245, v235, v231, v233
	v_lshl_add_u32 v229, v227, 3, 17
	v_cvt_f32_u32_e32 v229, v229
	v_mul_f32_e32 v229, 0xbed49a78, v229
	v_exp_f32_e32 v229, v229
	v_and_b32_e32 v234, 0xffff0000, v148
	v_and_b32_e32 v235, 0xffff0000, v156
	v_mul_f32_e32 v229, v240, v229
	v_mul_f32_e32 v234, v234, v242
	v_mul_f32_e32 v235, v235, v242
	v_fract_f32_e32 v229, v229
	v_mul_f32_e32 v234, v234, v183
	v_mul_f32_e32 v235, v235, v191
	v_sin_f32_e32 v230, v229
	v_cos_f32_e32 v231, v229
	s_nop 1
	v_mul_f32_e32 v236, v235, v230
	v_mul_f32_e32 v233, v234, v230
	v_fma_f32 v244, v234, v231, -v236
	v_fma_f32 v246, v235, v231, v233
	v_cvt_pk_bf16_f32 v148, v243, v244
	v_cvt_pk_bf16_f32 v156, v245, v246
	v_lshl_add_u32 v229, v227, 3, 18
	v_cvt_f32_u32_e32 v229, v229
	v_mul_f32_e32 v229, 0xbed49a78, v229
	v_exp_f32_e32 v229, v229
	v_lshlrev_b32_e32 v234, 16, v149
	v_lshlrev_b32_e32 v235, 16, v157
	v_mul_f32_e32 v229, v240, v229
	v_mul_f32_e32 v234, v234, v242
	v_mul_f32_e32 v235, v235, v242
	v_fract_f32_e32 v229, v229
	v_mul_f32_e32 v234, v234, v184
	v_mul_f32_e32 v235, v235, v192
	v_sin_f32_e32 v230, v229
	v_cos_f32_e32 v231, v229
	s_nop 1
	v_mul_f32_e32 v236, v235, v230
	v_mul_f32_e32 v233, v234, v230
	v_fma_f32 v243, v234, v231, -v236
	v_fma_f32 v245, v235, v231, v233
	v_lshl_add_u32 v229, v227, 3, 19
	v_cvt_f32_u32_e32 v229, v229
	v_mul_f32_e32 v229, 0xbed49a78, v229
	v_exp_f32_e32 v229, v229
	v_and_b32_e32 v234, 0xffff0000, v149
	v_and_b32_e32 v235, 0xffff0000, v157
	v_mul_f32_e32 v229, v240, v229
	v_mul_f32_e32 v234, v234, v242
	v_mul_f32_e32 v235, v235, v242
	v_fract_f32_e32 v229, v229
	v_mul_f32_e32 v234, v234, v185
	v_mul_f32_e32 v235, v235, v193
	v_sin_f32_e32 v230, v229
	v_cos_f32_e32 v231, v229
	s_nop 1
	v_mul_f32_e32 v236, v235, v230
	v_mul_f32_e32 v233, v234, v230
	v_fma_f32 v244, v234, v231, -v236
	v_fma_f32 v246, v235, v231, v233
	v_cvt_pk_bf16_f32 v149, v243, v244
	v_cvt_pk_bf16_f32 v157, v245, v246
	v_lshl_add_u32 v229, v227, 3, 20
	v_cvt_f32_u32_e32 v229, v229
	v_mul_f32_e32 v229, 0xbed49a78, v229
	v_exp_f32_e32 v229, v229
	v_lshlrev_b32_e32 v234, 16, v150
	v_lshlrev_b32_e32 v235, 16, v158
	v_mul_f32_e32 v229, v240, v229
	v_mul_f32_e32 v234, v234, v242
	v_mul_f32_e32 v235, v235, v242
	v_fract_f32_e32 v229, v229
	v_mul_f32_e32 v234, v234, v186
	v_mul_f32_e32 v235, v235, v194
	v_sin_f32_e32 v230, v229
	v_cos_f32_e32 v231, v229
	s_nop 1
	v_mul_f32_e32 v236, v235, v230
	v_mul_f32_e32 v233, v234, v230
	v_fma_f32 v243, v234, v231, -v236
	v_fma_f32 v245, v235, v231, v233
	v_lshl_add_u32 v229, v227, 3, 21
	v_cvt_f32_u32_e32 v229, v229
	v_mul_f32_e32 v229, 0xbed49a78, v229
	v_exp_f32_e32 v229, v229
	v_and_b32_e32 v234, 0xffff0000, v150
	v_and_b32_e32 v235, 0xffff0000, v158
	v_mul_f32_e32 v229, v240, v229
	v_mul_f32_e32 v234, v234, v242
	v_mul_f32_e32 v235, v235, v242
	v_fract_f32_e32 v229, v229
	v_mul_f32_e32 v234, v234, v187
	v_mul_f32_e32 v235, v235, v195
	v_sin_f32_e32 v230, v229
	v_cos_f32_e32 v231, v229
	s_nop 1
	v_mul_f32_e32 v236, v235, v230
	v_mul_f32_e32 v233, v234, v230
	v_fma_f32 v244, v234, v231, -v236
	v_fma_f32 v246, v235, v231, v233
	v_cvt_pk_bf16_f32 v150, v243, v244
	v_cvt_pk_bf16_f32 v158, v245, v246
	v_lshl_add_u32 v229, v227, 3, 22
	v_cvt_f32_u32_e32 v229, v229
	v_mul_f32_e32 v229, 0xbed49a78, v229
	v_exp_f32_e32 v229, v229
	v_lshlrev_b32_e32 v234, 16, v151
	v_lshlrev_b32_e32 v235, 16, v159
	v_mul_f32_e32 v229, v240, v229
	v_mul_f32_e32 v234, v234, v242
	v_mul_f32_e32 v235, v235, v242
	v_fract_f32_e32 v229, v229
	v_mul_f32_e32 v234, v234, v188
	v_mul_f32_e32 v235, v235, v196
	v_sin_f32_e32 v230, v229
	v_cos_f32_e32 v231, v229
	s_nop 1
	v_mul_f32_e32 v236, v235, v230
	v_mul_f32_e32 v233, v234, v230
	v_fma_f32 v243, v234, v231, -v236
	v_fma_f32 v245, v235, v231, v233
	v_lshl_add_u32 v229, v227, 3, 23
	v_cvt_f32_u32_e32 v229, v229
	v_mul_f32_e32 v229, 0xbed49a78, v229
	v_exp_f32_e32 v229, v229
	v_and_b32_e32 v234, 0xffff0000, v151
	v_and_b32_e32 v235, 0xffff0000, v159
	v_mul_f32_e32 v229, v240, v229
	v_mul_f32_e32 v234, v234, v242
	v_mul_f32_e32 v235, v235, v242
	v_fract_f32_e32 v229, v229
	v_mul_f32_e32 v234, v234, v189
	v_mul_f32_e32 v235, v235, v197
	v_sin_f32_e32 v230, v229
	v_cos_f32_e32 v231, v229
	s_nop 1
	v_mul_f32_e32 v236, v235, v230
	v_mul_f32_e32 v233, v234, v230
	v_fma_f32 v244, v234, v231, -v236
	v_fma_f32 v246, v235, v231, v233
	v_cvt_pk_bf16_f32 v151, v243, v244
	v_cvt_pk_bf16_f32 v159, v245, v246
	s_barrier
	s_cmp_lt_u32 s26, 4
	s_cbranch_scc1 .Lad_nostag
	s_barrier

; template <int DQK, int KA8, int DV, bool BIAS, bool JOINT>
; DI void attn_core(LAS unsigned char* lds, const bf16_t* Qrow, const bf16_t* KpA, int ldkA, const bf16_t* KpB, int ldkB, const bf16_t* Vp, int ldv,
;                   int qb, int wid, int lane, const float* qng  , f32x16 (&O)[DV / 32]) {
;     ...
;     for (int kt = 0; kt < nkt; ++kt) {
;         if (kt + 1 < nkt) gload(kt + 1);
;         if (JOINT && kt <= myc) {
;             LAS unsigned char* kb = lds + (kt & 1) * STG; LAS unsigned char* vb = kb + 64 * KROW;
;             const bool far = (kt * 64 + 63 - q0w <= -91);
;             f32x16 S0, S1;
; #pragma unroll
;             for (int i = 0; i < 16; ++i) { S0[i] = 0.f; S1[i] = 0.f; }
; #pragma unroll
;             for (int s = 0; s < DQK / 16; ++s) {
;                 const bf16x8 k0 = *(LAS const bf16x8*)(kb + koff + 32 * s), k1 = *(LAS const bf16x8*)(kb + koff + 32 * KROW + 32 * s);
;                 S0 = mfma32(k0, qf[s], S0); S1 = mfma32(k1, qf[s], S1);
;             }
;             if (BIAS && !far) {
;                 const int rb = kt * 64 - (q0w + l32) + 128;
; #pragma unroll
;                 for (int i = 0; i < 16; ++i) { const int i0 = rb + crow(i, hh); S0[i] += btab[i0 < 0 ? 0 : i0]; S1[i] += btab[i0 + 32 < 0 ? 0 : i0 + 32]; }
;             }
;             if (mnz) {
; #pragma unroll
;                 for (int i = 0; i < 16; ++i) { S0[i] -= m; S1[i] -= m; }
;             }
;             float mx = fmaxf(S0[0], S1[0]);
; #pragma unroll
;             for (int i = 1; i < 16; ++i) mx = fmaxf(mx, fmaxf(S0[i], S1[i]));
;             mx = fmaxf(mx, __shfl_xor(mx, 32));
;             if (__any(mx > 64.f || (kt == 0 && mx < -64.f))) {
;                 const float dm = (mx > 64.f || (kt == 0 && mx < -64.f)) ? mx : 0.f, alpha = __builtin_amdgcn_exp2f(-dm); m += dm; mnz = true;
;                 l *= alpha;
; #pragma unroll
;                 for (int dt = 0; dt < DV / 32; ++dt) O[dt] *= alpha;
; #pragma unroll
;                 for (int i = 0; i < 16; ++i) { S0[i] -= dm; S1[i] -= dm; }
;             }
;             float ps = 0.f;
; #pragma unroll
;             for (int i = 0; i < 16; ++i) { S0[i] = __builtin_amdgcn_exp2f(S0[i]); S1[i] = __builtin_amdgcn_exp2f(S1[i]); ps += S0[i] + S1[i]; }
;             l += ps;
; #pragma unroll
;             for (int half = 0; half < 2; ++half)
; #pragma unroll
;                 for (int s = 0; s < 2; ++s) {
.Lad_loop:
	s_add_i32 s58, s25, 1
	s_cmp_eq_u32 s24, 0
	s_cbranch_scc1 .Lad_x0_qk
	s_cmp_gt_u32 s24, s58
	s_cbranch_scc1 .Lad_x0_none
	s_cmp_eq_u32 s24, s58
	s_cbranch_scc1 .Lad_x0_pv
	ds_read_b64_tr_b16 v[182:183], v215 offset:20480
	ds_read_b64_tr_b16 v[184:185], v215 offset:23040
	ds_read_b64_tr_b16 v[186:187], v215 offset:20544
	ds_read_b64_tr_b16 v[188:189], v215 offset:23104
	ds_read_b64_tr_b16 v[190:191], v215 offset:20608
	ds_read_b64_tr_b16 v[192:193], v215 offset:23168
	ds_read_b64_tr_b16 v[194:195], v215 offset:20672
	ds_read_b64_tr_b16 v[196:197], v215 offset:23232
	ds_read_b64_tr_b16 v[198:199], v215 offset:25600
	ds_read_b64_tr_b16 v[200:201], v215 offset:28160
	ds_read_b64_tr_b16 v[202:203], v215 offset:25664
	ds_read_b64_tr_b16 v[204:205], v215 offset:28224
	s_waitcnt lgkmcnt(10)
	v_mfma_f32_32x32x16_bf16 v[0:15], v[182:185], v[96:99], v[0:15]
	ds_read_b64_tr_b16 v[206:207], v215 offset:25728
	ds_read_b64_tr_b16 v[208:209], v215 offset:28288
	s_waitcnt lgkmcnt(10)
	v_mfma_f32_32x32x16_bf16 v[16:31], v[186:189], v[96:99], v[16:31]
	ds_read_b64_tr_b16 v[210:211], v215 offset:25792
	ds_read_b64_tr_b16 v[212:213], v215 offset:28352
	s_waitcnt lgkmcnt(10)
	v_mfma_f32_32x32x16_bf16 v[32:47], v[190:193], v[96:99], v[32:47]
	ds_read_b64_tr_b16 v[182:183], v215 offset:30720
	ds_read_b64_tr_b16 v[184:185], v215 offset:33280
	s_waitcnt lgkmcnt(10)
	v_mfma_f32_32x32x16_bf16 v[48:63], v[194:197], v[96:99], v[48:63]
	s_waitcnt vmcnt(0)
	s_add_i32 s58, s24, 1
	s_cmp_lt_u32 s58, s17
	s_cbranch_scc0 .Lad_hv_1
	ds_write_b128 v253, v[160:163] offset:0
	ds_write_b128 v253, v[164:167] offset:12800
	ds_write_b128 v254, v[168:171] offset:0
.Lad_hv_1:
	ds_write_b128 v218, v[172:175] offset:0
	ds_write_b128 v218, v[176:179] offset:10240
	ds_read_b64_tr_b16 v[186:187], v215 offset:30784
	ds_read_b64_tr_b16 v[188:189], v215 offset:33344
	s_waitcnt lgkmcnt(12)
	v_mfma_f32_32x32x16_bf16 v[0:15], v[198:201], v[100:103], v[0:15]
	ds_read_b64_tr_b16 v[190:191], v215 offset:30848
	ds_read_b64_tr_b16 v[192:193], v215 offset:33408
	s_waitcnt lgkmcnt(12)
	v_mfma_f32_32x32x16_bf16 v[16:31], v[202:205], v[100:103], v[16:31]
	ds_read_b64_tr_b16 v[194:195], v215 offset:30912
	ds_read_b64_tr_b16 v[196:197], v215 offset:33472
	s_waitcnt lgkmcnt(12)
	v_mfma_f32_32x32x16_bf16 v[32:47], v[206:209], v[100:103], v[32:47]
	ds_read_b64_tr_b16 v[198:199], v215 offset:35840
	ds_read_b64_tr_b16 v[200:201], v215 offset:38400
	s_waitcnt lgkmcnt(12)
	v_mfma_f32_32x32x16_bf16 v[48:63], v[210:213], v[100:103], v[48:63]
	ds_read_b64_tr_b16 v[202:203], v215 offset:35904
	ds_read_b64_tr_b16 v[204:205], v215 offset:38464
	s_waitcnt lgkmcnt(12)
	v_mfma_f32_32x32x16_bf16 v[0:15], v[182:185], v[104:107], v[0:15]
	ds_read_b64_tr_b16 v[206:207], v215 offset:35968
	ds_read_b64_tr_b16 v[208:209], v215 offset:38528
	s_waitcnt lgkmcnt(10)
	v_mfma_f32_32x32x16_bf16 v[16:31], v[186:189], v[104:107], v[16:31]
	ds_read_b64_tr_b16 v[210:211], v215 offset:36032
	ds_read_b64_tr_b16 v[212:213], v215 offset:38592
	s_waitcnt lgkmcnt(10)
	v_mfma_f32_32x32x16_bf16 v[32:47], v[190:193], v[104:107], v[32:47]
	ds_read_b128 v[182:185], v214 offset:40960
	s_waitcnt lgkmcnt(9)
	v_mfma_f32_32x32x16_bf16 v[48:63], v[194:197], v[104:107], v[48:63]
	ds_read_b128 v[186:189], v214 offset:53760
	s_waitcnt lgkmcnt(8)
	v_mfma_f32_32x32x16_bf16 v[0:15], v[198:201], v[108:111], v[0:15]
	ds_read_b128 v[190:193], v214 offset:40992
	s_waitcnt lgkmcnt(7)
	v_mfma_f32_32x32x16_bf16 v[16:31], v[202:205], v[108:111], v[16:31]
	ds_read_b128 v[194:197], v214 offset:53792
	s_waitcnt lgkmcnt(6)
	v_mfma_f32_32x32x16_bf16 v[32:47], v[206:209], v[108:111], v[32:47]
	ds_read_b128 v[198:201], v214 offset:41024
	s_waitcnt lgkmcnt(5)
	v_mfma_f32_32x32x16_bf16 v[48:63], v[210:213], v[108:111], v[48:63]
	ds_read_b128 v[202:205], v214 offset:53824
	s_waitcnt lgkmcnt(5)
	v_mfma_f32_32x32x16_bf16 v[64:79], v[182:185], v[112:115], 0
	ds_read_b128 v[206:209], v214 offset:41056
	s_waitcnt lgkmcnt(5)
	v_mfma_f32_32x32x16_bf16 v[80:95], v[186:189], v[112:115], 0
	ds_read_b128 v[210:213], v214 offset:53856
	s_waitcnt lgkmcnt(5)
	v_mfma_f32_32x32x16_bf16 v[64:79], v[190:193], v[116:119], v[64:79]
	ds_read_b128 v[182:185], v214 offset:41088
	s_waitcnt lgkmcnt(5)
	v_mfma_f32_32x32x16_bf16 v[80:95], v[194:197], v[116:119], v[80:95]
	ds_read_b128 v[186:189], v214 offset:53888
	s_waitcnt lgkmcnt(5)
	v_mfma_f32_32x32x16_bf16 v[64:79], v[198:201], v[120:123], v[64:79]
	ds_read_b128 v[190:193], v214 offset:41120
	s_waitcnt lgkmcnt(5)
	v_mfma_f32_32x32x16_bf16 v[80:95], v[202:205], v[120:123], v[80:95]
	ds_read_b128 v[194:197], v214 offset:53920
	s_waitcnt lgkmcnt(5)
	v_mfma_f32_32x32x16_bf16 v[64:79], v[206:209], v[124:127], v[64:79]
	ds_read_b128 v[198:201], v214 offset:41152
	s_waitcnt lgkmcnt(5)
	v_mfma_f32_32x32x16_bf16 v[80:95], v[210:213], v[124:127], v[80:95]
	ds_read_b128 v[202:205], v214 offset:53952
	s_waitcnt lgkmcnt(5)
	v_mfma_f32_32x32x16_bf16 v[64:79], v[182:185], v[128:131], v[64:79]
	ds_read_b128 v[206:209], v214 offset:41184
	s_waitcnt lgkmcnt(5)
	v_mfma_f32_32x32x16_bf16 v[80:95], v[186:189], v[128:131], v[80:95]
	ds_read_b128 v[210:213], v214 offset:53984
	s_waitcnt lgkmcnt(5)
	v_mfma_f32_32x32x16_bf16 v[64:79], v[190:193], v[132:135], v[64:79]
	ds_read_b128 v[182:185], v214 offset:41216
	s_waitcnt lgkmcnt(5)
	v_mfma_f32_32x32x16_bf16 v[80:95], v[194:197], v[132:135], v[80:95]
	ds_read_b128 v[186:189], v214 offset:54016
	s_waitcnt lgkmcnt(5)
	v_mfma_f32_32x32x16_bf16 v[64:79], v[198:201], v[136:139], v[64:79]
	ds_read_b128 v[190:193], v214 offset:41248
	s_waitcnt lgkmcnt(5)
	v_mfma_f32_32x32x16_bf16 v[80:95], v[202:205], v[136:139], v[80:95]
	ds_read_b128 v[194:197], v214 offset:54048
	s_waitcnt lgkmcnt(5)
	v_mfma_f32_32x32x16_bf16 v[64:79], v[206:209], v[140:143], v[64:79]
	ds_read_b128 v[198:201], v214 offset:41280
	s_waitcnt lgkmcnt(5)
	v_mfma_f32_32x32x16_bf16 v[80:95], v[210:213], v[140:143], v[80:95]
	ds_read_b128 v[202:205], v214 offset:54080
	s_waitcnt lgkmcnt(5)
	v_mfma_f32_32x32x16_bf16 v[64:79], v[182:185], v[144:147], v[64:79]
	ds_read_b128 v[206:209], v214 offset:41312
	s_waitcnt lgkmcnt(5)
	v_mfma_f32_32x32x16_bf16 v[80:95], v[186:189], v[144:147], v[80:95]
	ds_read_b128 v[210:213], v214 offset:54112
	s_waitcnt lgkmcnt(5)
	v_mfma_f32_32x32x16_bf16 v[64:79], v[190:193], v[148:151], v[64:79]
	s_waitcnt lgkmcnt(4)
	v_mfma_f32_32x32x16_bf16 v[80:95], v[194:197], v[148:151], v[80:95]
	s_waitcnt lgkmcnt(3)
	v_mfma_f32_32x32x16_bf16 v[64:79], v[198:201], v[152:155], v[64:79]
	s_waitcnt lgkmcnt(2)
	v_mfma_f32_32x32x16_bf16 v[80:95], v[202:205], v[152:155], v[80:95]
	s_waitcnt lgkmcnt(1)
	v_mfma_f32_32x32x16_bf16 v[64:79], v[206:209], v[156:159], v[64:79]
	s_waitcnt lgkmcnt(0)
	v_mfma_f32_32x32x16_bf16 v[80:95], v[210:213], v[156:159], v[80:95]
	s_branch .Lad_x0_end
; #define LAS __attribute__((address_space(3)))
; DI unsigned pk2(float a, float b) { f32x2 v = {a, b}; bf16v2_t r = __builtin_convertvector(v, bf16v2_t); return __builtin_bit_cast(unsigned, r); }
; DI f32x16 mfma32(bf16x8 a, bf16x8 b, f32x16 c) { return __builtin_amdgcn_mfma_f32_32x32x16_bf16(a, b, c, 0, 0, 0); }
; DI s16x4 trread(LAS unsigned char* p) { return __builtin_amdgcn_ds_read_tr16_b64_v4i16((LAS s16x4*)p); }
; DI bf16x8 cat4(s16x4 lo, s16x4 hi) { return __builtin_shufflevector(lo, hi, 0, 1, 2, 3, 4, 5, 6, 7); }
; template <int DQK, int KA8, int DV, bool BIAS, bool JOINT>
; DI void attn_core(LAS unsigned char* lds, const bf16_t* Qrow, const bf16_t* KpA, int ldkA, const bf16_t* KpB, int ldkB, const bf16_t* Vp, int ldv,
;                   int qb, int wid, int lane, const float* qng  , f32x16 (&O)[DV / 32]) {
;     ...
;             for (int s = 0; s < DQK / 16; ++s) {
;                 const bf16x8 k0 = *(LAS const bf16x8*)(kb + koff + 32 * s), k1 = *(LAS const bf16x8*)(kb + koff + 32 * KROW + 32 * s);
;                 S0 = mfma32(k0, qf[s], S0); S1 = mfma32(k1, qf[s], S1);
;             }
;     ...
;             for (int half = 0; half < 2; ++half)
; #pragma unroll
;                 for (int s = 0; s < 2; ++s) {
;                     const f32x16& S = half ? S1 : S0;
;                     u32x4 pw; pw.x = pk2(S[8 * s], S[8 * s + 1]); pw.y = pk2(S[8 * s + 2], S[8 * s + 3]); pw.z = pk2(S[8 * s + 4], S[8 * s + 5]); pw.w = pk2(S[8 * s + 6], S[8 * s + 7]);
;                     const bf16x8 pf = __builtin_bit_cast(bf16x8, pw);
;                     LAS unsigned char* vr = vb + vtr + (32 * half + 16 * s) * VROW;
; #pragma unroll
;                     for (int dt = 0; dt < DV / 32; ++dt) {
;                         const bf16x8 vf = cat4(trread(vr + 64 * dt), trread(vr + 8 * VROW + 64 * dt));
;                         O[dt] = mfma32(vf, pf, O[dt]);
;                     }
.Lad_x0_pv:
	ds_read_b64_tr_b16 v[182:183], v215 offset:20480
	ds_read_b64_tr_b16 v[184:185], v215 offset:23040
	ds_read_b64_tr_b16 v[186:187], v215 offset:20544
	ds_read_b64_tr_b16 v[188:189], v215 offset:23104
	ds_read_b64_tr_b16 v[190:191], v215 offset:20608
	ds_read_b64_tr_b16 v[192:193], v215 offset:23168
	ds_read_b64_tr_b16 v[194:195], v215 offset:20672
	ds_read_b64_tr_b16 v[196:197], v215 offset:23232
	ds_read_b64_tr_b16 v[198:199], v215 offset:25600
	ds_read_b64_tr_b16 v[200:201], v215 offset:28160
	ds_read_b64_tr_b16 v[202:203], v215 offset:25664
	ds_read_b64_tr_b16 v[204:205], v215 offset:28224
	s_waitcnt lgkmcnt(10)
	v_mfma_f32_32x32x16_bf16 v[0:15], v[182:185], v[96:99], v[0:15]
	ds_read_b64_tr_b16 v[206:207], v215 offset:25728
	ds_read_b64_tr_b16 v[208:209], v215 offset:28288
	s_waitcnt lgkmcnt(10)
	v_mfma_f32_32x32x16_bf16 v[16:31], v[186:189], v[96:99], v[16:31]
	ds_read_b64_tr_b16 v[210:211], v215 offset:25792
	ds_read_b64_tr_b16 v[212:213], v215 offset:28352
	s_waitcnt lgkmcnt(10)
	v_mfma_f32_32x32x16_bf16 v[32:47], v[190:193], v[96:99], v[32:47]
	ds_read_b64_tr_b16 v[182:183], v215 offset:30720
	ds_read_b64_tr_b16 v[184:185], v215 offset:33280
	s_waitcnt lgkmcnt(10)
	v_mfma_f32_32x32x16_bf16 v[48:63], v[194:197], v[96:99], v[48:63]
	s_waitcnt vmcnt(0)
	s_add_i32 s58, s24, 1
	s_cmp_lt_u32 s58, s17
	s_cbranch_scc0 .Lad_hv_2
	ds_write_b128 v253, v[160:163] offset:0
	ds_write_b128 v253, v[164:167] offset:12800
	ds_write_b128 v254, v[168:171] offset:0
.Lad_hv_2:
	ds_write_b128 v218, v[172:175] offset:0
	ds_write_b128 v218, v[176:179] offset:10240
	ds_read_b64_tr_b16 v[186:187], v215 offset:30784
	ds_read_b64_tr_b16 v[188:189], v215 offset:33344
	s_waitcnt lgkmcnt(12)
	v_mfma_f32_32x32x16_bf16 v[0:15], v[198:201], v[100:103], v[0:15]
	ds_read_b64_tr_b16 v[190:191], v215 offset:30848
	ds_read_b64_tr_b16 v[192:193], v215 offset:33408
	s_waitcnt lgkmcnt(12)
	v_mfma_f32_32x32x16_bf16 v[16:31], v[202:205], v[100:103], v[16:31]
	ds_read_b64_tr_b16 v[194:195], v215 offset:30912
	ds_read_b64_tr_b16 v[196:197], v215 offset:33472
	s_waitcnt lgkmcnt(12)
	v_mfma_f32_32x32x16_bf16 v[32:47], v[206:209], v[100:103], v[32:47]
	ds_read_b64_tr_b16 v[198:199], v215 offset:35840
	ds_read_b64_tr_b16 v[200:201], v215 offset:38400
	s_waitcnt lgkmcnt(12)
	v_mfma_f32_32x32x16_bf16 v[48:63], v[210:213], v[100:103], v[48:63]
	ds_read_b64_tr_b16 v[202:203], v215 offset:35904
	ds_read_b64_tr_b16 v[204:205], v215 offset:38464
	s_waitcnt lgkmcnt(12)
	v_mfma_f32_32x32x16_bf16 v[0:15], v[182:185], v[104:107], v[0:15]
	ds_read_b64_tr_b16 v[206:207], v215 offset:35968
	ds_read_b64_tr_b16 v[208:209], v215 offset:38528
	s_waitcnt lgkmcnt(10)
	v_mfma_f32_32x32x16_bf16 v[16:31], v[186:189], v[104:107], v[16:31]
	ds_read_b64_tr_b16 v[210:211], v215 offset:36032
	ds_read_b64_tr_b16 v[212:213], v215 offset:38592
	s_waitcnt lgkmcnt(10)
	v_mfma_f32_32x32x16_bf16 v[32:47], v[190:193], v[104:107], v[32:47]
	s_waitcnt lgkmcnt(8)
	v_mfma_f32_32x32x16_bf16 v[48:63], v[194:197], v[104:107], v[48:63]
	s_waitcnt lgkmcnt(6)
	v_mfma_f32_32x32x16_bf16 v[0:15], v[198:201], v[108:111], v[0:15]
	s_waitcnt lgkmcnt(4)
	v_mfma_f32_32x32x16_bf16 v[16:31], v[202:205], v[108:111], v[16:31]
	s_waitcnt lgkmcnt(2)
	v_mfma_f32_32x32x16_bf16 v[32:47], v[206:209], v[108:111], v[32:47]
	s_waitcnt lgkmcnt(0)
	v_mfma_f32_32x32x16_bf16 v[48:63], v[210:213], v[108:111], v[48:63]
	s_branch .Lad_x0_end
.Lad_x0_qk:
	ds_read_b128 v[182:185], v214 offset:40960
	ds_read_b128 v[186:189], v214 offset:53760
	ds_read_b128 v[190:193], v214 offset:40992
	ds_read_b128 v[194:197], v214 offset:53792
	ds_read_b128 v[198:201], v214 offset:41024
	ds_read_b128 v[202:205], v214 offset:53824
	s_waitcnt lgkmcnt(5)
	v_mfma_f32_32x32x16_bf16 v[64:79], v[182:185], v[112:115], 0
	ds_read_b128 v[206:209], v214 offset:41056
	s_waitcnt lgkmcnt(5)
	v_mfma_f32_32x32x16_bf16 v[80:95], v[186:189], v[112:115], 0
	ds_read_b128 v[210:213], v214 offset:53856
	s_waitcnt lgkmcnt(5)
	v_mfma_f32_32x32x16_bf16 v[64:79], v[190:193], v[116:119], v[64:79]
	ds_read_b128 v[182:185], v214 offset:41088
	s_waitcnt lgkmcnt(5)
	v_mfma_f32_32x32x16_bf16 v[80:95], v[194:197], v[116:119], v[80:95]
	s_waitcnt vmcnt(0)
	s_add_i32 s58, s24, 1
	s_cmp_lt_u32 s58, s17
	s_cbranch_scc0 .Lad_hv_3
	ds_write_b128 v253, v[160:163] offset:0
	ds_write_b128 v253, v[164:167] offset:12800
	ds_write_b128 v254, v[168:171] offset:0
; #define LAS __attribute__((address_space(3)))
; template <int DQK, int KA8, int DV, bool BIAS, bool JOINT>
; DI void attn_core(LAS unsigned char* lds, const bf16_t* Qrow, const bf16_t* KpA, int ldkA, const bf16_t* KpB, int ldkB, const bf16_t* Vp, int ldv,
;                   int qb, int wid, int lane, const float* qng  , f32x16 (&O)[DV / 32]) {
;     ...
;     auto gload = [&](int kt) {
; #pragma unroll
;         for (int i = 0; i < NL; ++i) { const int c = tid + i * 512;
;             if (i * 512 < NKC) { const int row = c / KC, cc = c % KC;
;                 const bf16_t* src = (cc < KA8) ? KpA + (size_t)(kt * 64 + row) * ldkA + cc * 8 : KpB + (size_t)(kt * 64 + row) * ldkB + (cc - KA8) * 8;
;                 stg[i] = *(const u32x4*)src; }
;             else { const int c2 = c - NKC, row = c2 / VC, cc = c2 % VC; stg[i] = *(const u32x4*)(Vp + (size_t)(kt * 64 + row) * ldv + cc * 8); } }
;     };
;     auto lstore = [&](int buf) {
; #pragma unroll
;         for (int i = 0; i < NL; ++i) { const int c = tid + i * 512;
;             if (i * 512 < NKC) { const int row = c / KC, cc = c % KC; *(LAS u32x4*)(lds + buf * STG + row * KROW + cc * 16) = stg[i]; }
;             else { const int c2 = c - NKC, row = c2 / VC, cc = c2 % VC; *(LAS u32x4*)(lds + buf * STG + 64 * KROW + row * VROW + cc * 16) = stg[i]; } }
;     };
;     gload(0); lstore(0); __syncthreads();
;     for (int kt = 0; kt < nkt; ++kt) {
;         if (kt + 1 < nkt) gload(kt + 1);
;         if (JOINT && kt <= myc) {
;             LAS unsigned char* kb = lds + (kt & 1) * STG; LAS unsigned char* vb = kb + 64 * KROW;
;             const bool far = (kt * 64 + 63 - q0w <= -91);
;             f32x16 S0, S1;
; #pragma unroll
;             for (int i = 0; i < 16; ++i) { S0[i] = 0.f; S1[i] = 0.f; }
; #pragma unroll
;             for (int s = 0; s < DQK / 16; ++s) {
;                 const bf16x8 k0 = *(LAS const bf16x8*)(kb + koff + 32 * s), k1 = *(LAS const bf16x8*)(kb + koff + 32 * KROW + 32 * s);
;                 S0 = mfma32(k0, qf[s], S0); S1 = mfma32(k1, qf[s], S1);
;             }
;             if (BIAS && !far) {
;                 const int rb = kt * 64 - (q0w + l32) + 128;
; #pragma unroll
;                 for (int i = 0; i < 16; ++i) { const int i0 = rb + crow(i, hh); S0[i] += btab[i0 < 0 ? 0 : i0]; S1[i] += btab[i0 + 32 < 0 ? 0 : i0 + 32]; }
;             }
;             if (mnz) {
; #pragma unroll
.Lad_hv_3:
	ds_write_b128 v218, v[172:175] offset:0
	ds_write_b128 v218, v[176:179] offset:10240
	ds_read_b128 v[186:189], v214 offset:53888
	s_waitcnt lgkmcnt(7)
	v_mfma_f32_32x32x16_bf16 v[64:79], v[198:201], v[120:123], v[64:79]
	ds_read_b128 v[190:193], v214 offset:41120
	s_waitcnt lgkmcnt(7)
	v_mfma_f32_32x32x16_bf16 v[80:95], v[202:205], v[120:123], v[80:95]
	ds_read_b128 v[194:197], v214 offset:53920
	s_waitcnt lgkmcnt(7)
	v_mfma_f32_32x32x16_bf16 v[64:79], v[206:209], v[124:127], v[64:79]
	ds_read_b128 v[198:201], v214 offset:41152
	s_waitcnt lgkmcnt(7)
	v_mfma_f32_32x32x16_bf16 v[80:95], v[210:213], v[124:127], v[80:95]
	ds_read_b128 v[202:205], v214 offset:53952
	s_waitcnt lgkmcnt(7)
	v_mfma_f32_32x32x16_bf16 v[64:79], v[182:185], v[128:131], v[64:79]
	ds_read_b128 v[206:209], v214 offset:41184
	s_waitcnt lgkmcnt(5)
	v_mfma_f32_32x32x16_bf16 v[80:95], v[186:189], v[128:131], v[80:95]
	ds_read_b128 v[210:213], v214 offset:53984
	s_waitcnt lgkmcnt(5)
	v_mfma_f32_32x32x16_bf16 v[64:79], v[190:193], v[132:135], v[64:79]
	ds_read_b128 v[182:185], v214 offset:41216
	s_waitcnt lgkmcnt(5)
	v_mfma_f32_32x32x16_bf16 v[80:95], v[194:197], v[132:135], v[80:95]
	ds_read_b128 v[186:189], v214 offset:54016
	s_waitcnt lgkmcnt(5)
	v_mfma_f32_32x32x16_bf16 v[64:79], v[198:201], v[136:139], v[64:79]
	ds_read_b128 v[190:193], v214 offset:41248
	s_waitcnt lgkmcnt(5)
	v_mfma_f32_32x32x16_bf16 v[80:95], v[202:205], v[136:139], v[80:95]
	ds_read_b128 v[194:197], v214 offset:54048
	s_waitcnt lgkmcnt(5)
	v_mfma_f32_32x32x16_bf16 v[64:79], v[206:209], v[140:143], v[64:79]
	ds_read_b128 v[198:201], v214 offset:41280
	s_waitcnt lgkmcnt(5)
	v_mfma_f32_32x32x16_bf16 v[80:95], v[210:213], v[140:143], v[80:95]
	ds_read_b128 v[202:205], v214 offset:54080
	s_waitcnt lgkmcnt(5)
	v_mfma_f32_32x32x16_bf16 v[64:79], v[182:185], v[144:147], v[64:79]
	ds_read_b128 v[206:209], v214 offset:41312
	s_waitcnt lgkmcnt(5)
	v_mfma_f32_32x32x16_bf16 v[80:95], v[186:189], v[144:147], v[80:95]
	ds_read_b128 v[210:213], v214 offset:54112
	s_waitcnt lgkmcnt(5)
	v_mfma_f32_32x32x16_bf16 v[64:79], v[190:193], v[148:151], v[64:79]
	s_waitcnt lgkmcnt(4)
	v_mfma_f32_32x32x16_bf16 v[80:95], v[194:197], v[148:151], v[80:95]
	s_waitcnt lgkmcnt(3)
	v_mfma_f32_32x32x16_bf16 v[64:79], v[198:201], v[152:155], v[64:79]
	s_waitcnt lgkmcnt(2)
	v_mfma_f32_32x32x16_bf16 v[80:95], v[202:205], v[152:155], v[80:95]
	s_waitcnt lgkmcnt(1)
	v_mfma_f32_32x32x16_bf16 v[64:79], v[206:209], v[156:159], v[64:79]
	s_waitcnt lgkmcnt(0)
	v_mfma_f32_32x32x16_bf16 v[80:95], v[210:213], v[156:159], v[80:95]
	s_branch .Lad_x0_end
.Lad_x0_none:
	s_waitcnt vmcnt(0)
	s_add_i32 s58, s24, 1
	s_cmp_lt_u32 s58, s17
	s_cbranch_scc0 .Lad_hv_4
	ds_write_b128 v253, v[160:163] offset:0
	ds_write_b128 v253, v[164:167] offset:12800
	ds_write_b128 v254, v[168:171] offset:0
.Lad_hv_4:
	ds_write_b128 v218, v[172:175] offset:0
	ds_write_b128 v218, v[176:179] offset:10240
.Lad_x0_end:
	s_waitcnt lgkmcnt(0)
	s_barrier
	s_add_i32 s58, s24, 1
	s_cmp_lt_u32 s58, s17
	s_cbranch_scc0 .Lad_y0_nold
	global_load_dwordx4 v[172:175], v222, s[34:35]
	global_load_dwordx4 v[176:179], v223, s[34:35]
	s_add_u32 s34, s34, 0xe0000
	s_addc_u32 s35, s35, 0
	s_add_i32 s58, s24, 2
	s_cmp_lt_u32 s58, s17
	s_cbranch_scc0 .Lad_y0_nold
	global_load_dwordx4 v[160:163], v219, s[30:31]
	global_load_dwordx4 v[164:167], v220, s[30:31]
	global_load_dwordx4 v[168:171], v221, s[36:37]
	s_add_u32 s30, s30, 0xe0000
	s_addc_u32 s31, s31, 0
	s_add_u32 s36, s36, 0x22000
	s_addc_u32 s37, s37, 0
.Lad_y0_nold:
	s_cmp_gt_u32 s24, s25
	s_cbranch_scc1 .Lad_y0_end
	s_nop 15
	s_cmp_eq_u32 s40, 0
	s_cbranch_scc1 .Lad_y0_nosubm
	v_sub_f32_e32 v64, v64, v224
	v_sub_f32_e32 v65, v65, v224
	v_sub_f32_e32 v66, v66, v224
	v_sub_f32_e32 v67, v67, v224
	v_sub_f32_e32 v68, v68, v224
	v_sub_f32_e32 v69, v69, v224
	v_sub_f32_e32 v70, v70, v224
	v_sub_f32_e32 v71, v71, v224
	v_sub_f32_e32 v72, v72, v224
	v_sub_f32_e32 v73, v73, v224
	v_sub_f32_e32 v74, v74, v224
	v_sub_f32_e32 v75, v75, v224
	v_sub_f32_e32 v76, v76, v224
	v_sub_f32_e32 v77, v77, v224
	v_sub_f32_e32 v78, v78, v224
	v_sub_f32_e32 v79, v79, v224
	v_sub_f32_e32 v80, v80, v224
	v_sub_f32_e32 v81, v81, v224
	v_sub_f32_e32 v82, v82, v224
	v_sub_f32_e32 v83, v83, v224
	v_sub_f32_e32 v84, v84, v224
	v_sub_f32_e32 v85, v85, v224
	v_sub_f32_e32 v86, v86, v224
	v_sub_f32_e32 v87, v87, v224
	v_sub_f32_e32 v88, v88, v224
	v_sub_f32_e32 v89, v89, v224
	v_sub_f32_e32 v90, v90, v224
	v_sub_f32_e32 v91, v91, v224
	v_sub_f32_e32 v92, v92, v224
	v_sub_f32_e32 v93, v93, v224
	v_sub_f32_e32 v94, v94, v224
	v_sub_f32_e32 v95, v95, v224
.Lad_y0_nosubm:
	v_max3_f32 v229, v64, v65, v66
	v_max3_f32 v232, v67, v68, v69
	v_max3_f32 v233, v70, v71, v72
	v_max3_f32 v234, v73, v74, v75
	v_max3_f32 v229, v229, v76, v77
	v_max3_f32 v232, v232, v78, v79
	v_max3_f32 v233, v233, v80, v81
	v_max3_f32 v234, v234, v82, v83
	v_max3_f32 v229, v229, v84, v85
	v_max3_f32 v232, v232, v86, v87
	v_max3_f32 v233, v233, v88, v89
	v_max3_f32 v234, v234, v90, v91
	v_max3_f32 v229, v229, v92, v93
	v_max3_f32 v232, v232, v94, v95
	v_max3_f32 v229, v229, v232, v233
	v_max_f32_e32 v229, v229, v234
	v_mov_b32_e32 v230, v229
	v_mov_b32_e32 v231, v229
	s_nop 1
	v_permlane32_swap_b32_e32 v230, v231
	s_nop 1
	v_max_f32_e32 v229, v230, v231
	v_cmp_lt_f32_e32 vcc, 0x42800000, v229
	s_cmp_lg_u32 s24, 0
	s_cbranch_scc1 .Lad_y0_notfirst
	v_mov_b32_e32 v232, 0xc2800000
	v_cmp_lt_f32_e64 s[44:45], v229, v232
	s_or_b64 vcc, vcc, s[44:45]
; DI unsigned pk2(float a, float b) { f32x2 v = {a, b}; bf16v2_t r = __builtin_convertvector(v, bf16v2_t); return __builtin_bit_cast(unsigned, r); }
; template <int DQK, int KA8, int DV, bool BIAS, bool JOINT>
; DI void attn_core(LAS unsigned char* lds, const bf16_t* Qrow, const bf16_t* KpA, int ldkA, const bf16_t* KpB, int ldkB, const bf16_t* Vp, int ldv,
;                   int qb, int wid, int lane, const float* qng  , f32x16 (&O)[DV / 32]) {
;     ...
;             if (__any(mx > 64.f || (kt == 0 && mx < -64.f))) {
;                 const float dm = (mx > 64.f || (kt == 0 && mx < -64.f)) ? mx : 0.f, alpha = __builtin_amdgcn_exp2f(-dm); m += dm; mnz = true;
;                 l *= alpha;
; #pragma unroll
;                 for (int dt = 0; dt < DV / 32; ++dt) O[dt] *= alpha;
; #pragma unroll
;                 for (int i = 0; i < 16; ++i) { S0[i] -= dm; S1[i] -= dm; }
;             }
;             float ps = 0.f;
; #pragma unroll
;             for (int i = 0; i < 16; ++i) { S0[i] = __builtin_amdgcn_exp2f(S0[i]); S1[i] = __builtin_amdgcn_exp2f(S1[i]); ps += S0[i] + S1[i]; }
;             l += ps;
; #pragma unroll
;             for (int half = 0; half < 2; ++half)
; #pragma unroll
;                 for (int s = 0; s < 2; ++s) {
;                     const f32x16& S = half ? S1 : S0;
;                     u32x4 pw; pw.x = pk2(S[8 * s], S[8 * s + 1]); pw.y = pk2(S[8 * s + 2], S[8 * s + 3]); pw.z = pk2(S[8 * s + 4], S[8 * s + 5]); pw.w = pk2(S[8 * s + 6], S[8 * s + 7]);
;                     const bf16x8 pf = __builtin_bit_cast(bf16x8, pw);
.Lad_y0_notfirst:
	s_cmp_lg_u64 vcc, 0
	s_cbranch_scc0 .Lad_y0_noresc
	s_nop 3
	v_cndmask_b32_e32 v232, 0, v229, vcc
	v_exp_f32_e64 v233, -v232
	v_add_f32_e32 v224, v224, v232
	s_mov_b32 s40, 1
	v_mul_f32_e32 v225, v225, v233
	v_mul_f32_e32 v0, v0, v233
	v_mul_f32_e32 v1, v1, v233
	v_mul_f32_e32 v2, v2, v233
	v_mul_f32_e32 v3, v3, v233
	v_mul_f32_e32 v4, v4, v233
	v_mul_f32_e32 v5, v5, v233
	v_mul_f32_e32 v6, v6, v233
	v_mul_f32_e32 v7, v7, v233
	v_mul_f32_e32 v8, v8, v233
	v_mul_f32_e32 v9, v9, v233
	v_mul_f32_e32 v10, v10, v233
	v_mul_f32_e32 v11, v11, v233
	v_mul_f32_e32 v12, v12, v233
	v_mul_f32_e32 v13, v13, v233
	v_mul_f32_e32 v14, v14, v233
	v_mul_f32_e32 v15, v15, v233
	v_mul_f32_e32 v16, v16, v233
	v_mul_f32_e32 v17, v17, v233
	v_mul_f32_e32 v18, v18, v233
	v_mul_f32_e32 v19, v19, v233
	v_mul_f32_e32 v20, v20, v233
	v_mul_f32_e32 v21, v21, v233
	v_mul_f32_e32 v22, v22, v233
	v_mul_f32_e32 v23, v23, v233
	v_mul_f32_e32 v24, v24, v233
	v_mul_f32_e32 v25, v25, v233
	v_mul_f32_e32 v26, v26, v233
	v_mul_f32_e32 v27, v27, v233
	v_mul_f32_e32 v28, v28, v233
	v_mul_f32_e32 v29, v29, v233
	v_mul_f32_e32 v30, v30, v233
	v_mul_f32_e32 v31, v31, v233
	v_mul_f32_e32 v32, v32, v233
	v_mul_f32_e32 v33, v33, v233
	v_mul_f32_e32 v34, v34, v233
	v_mul_f32_e32 v35, v35, v233
	v_mul_f32_e32 v36, v36, v233
	v_mul_f32_e32 v37, v37, v233
	v_mul_f32_e32 v38, v38, v233
	v_mul_f32_e32 v39, v39, v233
	v_mul_f32_e32 v40, v40, v233
	v_mul_f32_e32 v41, v41, v233
	v_mul_f32_e32 v42, v42, v233
	v_mul_f32_e32 v43, v43, v233
	v_mul_f32_e32 v44, v44, v233
	v_mul_f32_e32 v45, v45, v233
	v_mul_f32_e32 v46, v46, v233
	v_mul_f32_e32 v47, v47, v233
	v_mul_f32_e32 v48, v48, v233
	v_mul_f32_e32 v49, v49, v233
	v_mul_f32_e32 v50, v50, v233
	v_mul_f32_e32 v51, v51, v233
	v_mul_f32_e32 v52, v52, v233
	v_mul_f32_e32 v53, v53, v233
	v_mul_f32_e32 v54, v54, v233
	v_mul_f32_e32 v55, v55, v233
	v_mul_f32_e32 v56, v56, v233
	v_mul_f32_e32 v57, v57, v233
	v_mul_f32_e32 v58, v58, v233
	v_mul_f32_e32 v59, v59, v233
	v_mul_f32_e32 v60, v60, v233
	v_mul_f32_e32 v61, v61, v233
	v_mul_f32_e32 v62, v62, v233
	v_mul_f32_e32 v63, v63, v233
	v_sub_f32_e32 v64, v64, v232
	v_sub_f32_e32 v65, v65, v232
	v_sub_f32_e32 v66, v66, v232
	v_sub_f32_e32 v67, v67, v232
	v_sub_f32_e32 v68, v68, v232
	v_sub_f32_e32 v69, v69, v232
	v_sub_f32_e32 v70, v70, v232
	v_sub_f32_e32 v71, v71, v232
	v_sub_f32_e32 v72, v72, v232
	v_sub_f32_e32 v73, v73, v232
	v_sub_f32_e32 v74, v74, v232
	v_sub_f32_e32 v75, v75, v232
	v_sub_f32_e32 v76, v76, v232
	v_sub_f32_e32 v77, v77, v232
	v_sub_f32_e32 v78, v78, v232
	v_sub_f32_e32 v79, v79, v232
	v_sub_f32_e32 v80, v80, v232
	v_sub_f32_e32 v81, v81, v232
	v_sub_f32_e32 v82, v82, v232
	v_sub_f32_e32 v83, v83, v232
	v_sub_f32_e32 v84, v84, v232
	v_sub_f32_e32 v85, v85, v232
	v_sub_f32_e32 v86, v86, v232
	v_sub_f32_e32 v87, v87, v232
	v_sub_f32_e32 v88, v88, v232
	v_sub_f32_e32 v89, v89, v232
	v_sub_f32_e32 v90, v90, v232
	v_sub_f32_e32 v91, v91, v232
	v_sub_f32_e32 v92, v92, v232
	v_sub_f32_e32 v93, v93, v232
	v_sub_f32_e32 v94, v94, v232
	v_sub_f32_e32 v95, v95, v232
.Lad_y0_noresc:
	v_exp_f32_e32 v64, v64
	v_exp_f32_e32 v65, v65
	v_exp_f32_e32 v66, v66
	v_exp_f32_e32 v67, v67
	v_exp_f32_e32 v68, v68
	v_exp_f32_e32 v69, v69
	v_exp_f32_e32 v70, v70
	v_exp_f32_e32 v71, v71
	v_exp_f32_e32 v72, v72
	v_exp_f32_e32 v73, v73
	v_exp_f32_e32 v74, v74
	v_exp_f32_e32 v75, v75
	v_exp_f32_e32 v76, v76
	v_exp_f32_e32 v77, v77
	v_exp_f32_e32 v78, v78
	v_exp_f32_e32 v79, v79
	v_exp_f32_e32 v80, v80
	v_exp_f32_e32 v81, v81
	v_exp_f32_e32 v82, v82
	v_exp_f32_e32 v83, v83
	v_exp_f32_e32 v84, v84
	v_exp_f32_e32 v85, v85
	v_exp_f32_e32 v86, v86
	v_exp_f32_e32 v87, v87
	v_exp_f32_e32 v88, v88
	v_exp_f32_e32 v89, v89
	v_exp_f32_e32 v90, v90
	v_exp_f32_e32 v91, v91
	v_exp_f32_e32 v92, v92
	v_exp_f32_e32 v93, v93
	v_exp_f32_e32 v94, v94
	v_exp_f32_e32 v95, v95
	v_add_f32_e32 v229, v64, v65
	v_add_f32_e32 v232, v66, v67
	v_add_f32_e32 v233, v68, v69
	v_add_f32_e32 v234, v70, v71
	v_add_f32_e32 v229, v229, v72
	v_add_f32_e32 v232, v232, v73
	v_add_f32_e32 v233, v233, v74
	v_add_f32_e32 v234, v234, v75
	v_add_f32_e32 v229, v229, v76
	v_add_f32_e32 v232, v232, v77
	v_add_f32_e32 v233, v233, v78
	v_add_f32_e32 v234, v234, v79
	v_add_f32_e32 v229, v229, v80
	v_add_f32_e32 v232, v232, v81
	v_add_f32_e32 v233, v233, v82
	v_add_f32_e32 v234, v234, v83
	v_add_f32_e32 v229, v229, v84
	v_add_f32_e32 v232, v232, v85
	v_add_f32_e32 v233, v233, v86
	v_add_f32_e32 v234, v234, v87
	v_add_f32_e32 v229, v229, v88
	v_add_f32_e32 v232, v232, v89
	v_add_f32_e32 v233, v233, v90
	v_add_f32_e32 v234, v234, v91
	v_add_f32_e32 v229, v229, v92
	v_add_f32_e32 v232, v232, v93
	v_add_f32_e32 v233, v233, v94
	v_add_f32_e32 v234, v234, v95
	v_add_f32_e32 v229, v229, v232
	v_add_f32_e32 v233, v233, v234
	v_add_f32_e32 v229, v229, v233
	v_add_f32_e32 v225, v225, v229
	v_cvt_pk_bf16_f32 v96, v64, v65
	v_cvt_pk_bf16_f32 v97, v66, v67
	v_cvt_pk_bf16_f32 v98, v68, v69
	v_cvt_pk_bf16_f32 v99, v70, v71
	v_cvt_pk_bf16_f32 v100, v72, v73
	v_cvt_pk_bf16_f32 v101, v74, v75
	v_cvt_pk_bf16_f32 v102, v76, v77
	v_cvt_pk_bf16_f32 v103, v78, v79
	v_cvt_pk_bf16_f32 v104, v80, v81
	v_cvt_pk_bf16_f32 v105, v82, v83
	v_cvt_pk_bf16_f32 v106, v84, v85
	v_cvt_pk_bf16_f32 v107, v86, v87
	v_cvt_pk_bf16_f32 v108, v88, v89
	v_cvt_pk_bf16_f32 v109, v90, v91
	v_cvt_pk_bf16_f32 v110, v92, v93
	v_cvt_pk_bf16_f32 v111, v94, v95
; template <int DQK, int KA8, int DV, bool BIAS, bool JOINT>
; DI void attn_core(LAS unsigned char* lds, const bf16_t* Qrow, const bf16_t* KpA, int ldkA, const bf16_t* KpB, int ldkB, const bf16_t* Vp, int ldv,
;                   int qb, int wid, int lane, const float* qng  , f32x16 (&O)[DV / 32]) {
;     ...
;             for (int s = 0; s < DQK / 16; ++s) {
;                 const bf16x8 k0 = *(LAS const bf16x8*)(kb + koff + 32 * s), k1 = *(LAS const bf16x8*)(kb + koff + 32 * KROW + 32 * s);
;                 S0 = mfma32(k0, qf[s], S0); S1 = mfma32(k1, qf[s], S1);
;             }
;             if (BIAS && !far) {
;                 const int rb = kt * 64 - (q0w + l32) + 128;
; #pragma unroll
;                 for (int i = 0; i < 16; ++i) { const int i0 = rb + crow(i, hh); S0[i] += btab[i0 < 0 ? 0 : i0]; S1[i] += btab[i0 + 32 < 0 ? 0 : i0 + 32]; }
;             }
;             if (mnz) {
; #pragma unroll
;                 for (int i = 0; i < 16; ++i) { S0[i] -= m; S1[i] -= m; }
;             }
;             float mx = fmaxf(S0[0], S1[0]);
; #pragma unroll
;             for (int i = 1; i < 16; ++i) mx = fmaxf(mx, fmaxf(S0[i], S1[i]));
;             mx = fmaxf(mx, __shfl_xor(mx, 32));
;             if (__any(mx > 64.f || (kt == 0 && mx < -64.f))) {
;                 const float dm = (mx > 64.f || (kt == 0 && mx < -64.f)) ? mx : 0.f, alpha = __builtin_amdgcn_exp2f(-dm); m += dm; mnz = true;
;                 l *= alpha;
; #pragma unroll
;                 for (int dt = 0; dt < DV / 32; ++dt) O[dt] *= alpha;
; #pragma unroll
;                 for (int i = 0; i < 16; ++i) { S0[i] -= dm; S1[i] -= dm; }
;             }
;             float ps = 0.f;
; #pragma unroll
;             for (int i = 0; i < 16; ++i) { S0[i] = __builtin_amdgcn_exp2f(S0[i]); S1[i] = __builtin_amdgcn_exp2f(S1[i]); ps += S0[i] + S1[i]; }
;             l += ps;
; #pragma unroll
;             for (int half = 0; half < 2; ++half)
; #pragma unroll
;                 for (int s = 0; s < 2; ++s) {
;                     const f32x16& S = half ? S1 : S0;
;                     u32x4 pw; pw.x = pk2(S[8 * s], S[8 * s + 1]); pw.y = pk2(S[8 * s + 2], S[8 * s + 3]); pw.z = pk2(S[8 * s + 4], S[8 * s + 5]); pw.w = pk2(S[8 * s + 6], S[8 * s + 7]);
;                     const bf16x8 pf = __builtin_bit_cast(bf16x8, pw);
;                     LAS unsigned char* vr = vb + vtr + (32 * half + 16 * s) * VROW;
; #pragma unroll
.Lad_y0_end:
	s_barrier
	s_add_i32 s59, s24, 1
	s_add_i32 s58, s25, 1
	s_cmp_gt_u32 s59, s58
	s_cbranch_scc1 .Lad_x1_none
	s_cmp_eq_u32 s59, s58
	s_cbranch_scc1 .Lad_x1_pv
	ds_read_b64_tr_b16 v[182:183], v215 offset:0
	ds_read_b64_tr_b16 v[184:185], v215 offset:2560
	ds_read_b64_tr_b16 v[186:187], v215 offset:64
	ds_read_b64_tr_b16 v[188:189], v215 offset:2624
	ds_read_b64_tr_b16 v[190:191], v215 offset:128
	ds_read_b64_tr_b16 v[192:193], v215 offset:2688
	ds_read_b64_tr_b16 v[194:195], v215 offset:192
	ds_read_b64_tr_b16 v[196:197], v215 offset:2752
	ds_read_b64_tr_b16 v[198:199], v215 offset:5120
	ds_read_b64_tr_b16 v[200:201], v215 offset:7680
	ds_read_b64_tr_b16 v[202:203], v215 offset:5184
	ds_read_b64_tr_b16 v[204:205], v215 offset:7744
	s_waitcnt lgkmcnt(10)
	v_mfma_f32_32x32x16_bf16 v[0:15], v[182:185], v[96:99], v[0:15]
	ds_read_b64_tr_b16 v[206:207], v215 offset:5248
	ds_read_b64_tr_b16 v[208:209], v215 offset:7808
	s_waitcnt lgkmcnt(10)
	v_mfma_f32_32x32x16_bf16 v[16:31], v[186:189], v[96:99], v[16:31]
	ds_read_b64_tr_b16 v[210:211], v215 offset:5312
	ds_read_b64_tr_b16 v[212:213], v215 offset:7872
	s_waitcnt lgkmcnt(10)
	v_mfma_f32_32x32x16_bf16 v[32:47], v[190:193], v[96:99], v[32:47]
	ds_read_b64_tr_b16 v[182:183], v215 offset:10240
	ds_read_b64_tr_b16 v[184:185], v215 offset:12800
	s_waitcnt lgkmcnt(10)
	v_mfma_f32_32x32x16_bf16 v[48:63], v[194:197], v[96:99], v[48:63]
	s_waitcnt vmcnt(0)
	s_add_i32 s58, s59, 1
	s_cmp_lt_u32 s58, s17
	s_cbranch_scc0 .Lad_hv_5
	ds_write_b128 v216, v[160:163] offset:40960
	ds_write_b128 v216, v[164:167] offset:53760
	ds_write_b128 v217, v[168:171] offset:40960
.Lad_hv_5:
	ds_write_b128 v218, v[172:175] offset:20480
	ds_write_b128 v218, v[176:179] offset:30720
	ds_read_b64_tr_b16 v[186:187], v215 offset:10304
	ds_read_b64_tr_b16 v[188:189], v215 offset:12864
	s_waitcnt lgkmcnt(12)
	v_mfma_f32_32x32x16_bf16 v[0:15], v[198:201], v[100:103], v[0:15]
	ds_read_b64_tr_b16 v[190:191], v215 offset:10368
	ds_read_b64_tr_b16 v[192:193], v215 offset:12928
	s_waitcnt lgkmcnt(12)
	v_mfma_f32_32x32x16_bf16 v[16:31], v[202:205], v[100:103], v[16:31]
	ds_read_b64_tr_b16 v[194:195], v215 offset:10432
	ds_read_b64_tr_b16 v[196:197], v215 offset:12992
	s_waitcnt lgkmcnt(12)
	v_mfma_f32_32x32x16_bf16 v[32:47], v[206:209], v[100:103], v[32:47]
	ds_read_b64_tr_b16 v[198:199], v215 offset:15360
	ds_read_b64_tr_b16 v[200:201], v215 offset:17920
	s_waitcnt lgkmcnt(12)
	v_mfma_f32_32x32x16_bf16 v[48:63], v[210:213], v[100:103], v[48:63]
	ds_read_b64_tr_b16 v[202:203], v215 offset:15424
	ds_read_b64_tr_b16 v[204:205], v215 offset:17984
	s_waitcnt lgkmcnt(12)
	v_mfma_f32_32x32x16_bf16 v[0:15], v[182:185], v[104:107], v[0:15]
	ds_read_b64_tr_b16 v[206:207], v215 offset:15488
	ds_read_b64_tr_b16 v[208:209], v215 offset:18048
	s_waitcnt lgkmcnt(10)
	v_mfma_f32_32x32x16_bf16 v[16:31], v[186:189], v[104:107], v[16:31]
	ds_read_b64_tr_b16 v[210:211], v215 offset:15552
	ds_read_b64_tr_b16 v[212:213], v215 offset:18112
	s_waitcnt lgkmcnt(10)
	v_mfma_f32_32x32x16_bf16 v[32:47], v[190:193], v[104:107], v[32:47]
	ds_read_b128 v[182:185], v252 offset:0
	s_waitcnt lgkmcnt(9)
	v_mfma_f32_32x32x16_bf16 v[48:63], v[194:197], v[104:107], v[48:63]
	ds_read_b128 v[186:189], v252 offset:12800
	s_waitcnt lgkmcnt(8)
	v_mfma_f32_32x32x16_bf16 v[0:15], v[198:201], v[108:111], v[0:15]
	ds_read_b128 v[190:193], v252 offset:32
	s_waitcnt lgkmcnt(7)
	v_mfma_f32_32x32x16_bf16 v[16:31], v[202:205], v[108:111], v[16:31]
	ds_read_b128 v[194:197], v252 offset:12832
	s_waitcnt lgkmcnt(6)
	v_mfma_f32_32x32x16_bf16 v[32:47], v[206:209], v[108:111], v[32:47]
	ds_read_b128 v[198:201], v252 offset:64
	s_waitcnt lgkmcnt(5)
	v_mfma_f32_32x32x16_bf16 v[48:63], v[210:213], v[108:111], v[48:63]
	ds_read_b128 v[202:205], v252 offset:12864
	s_waitcnt lgkmcnt(5)
	v_mfma_f32_32x32x16_bf16 v[64:79], v[182:185], v[112:115], 0
	ds_read_b128 v[206:209], v252 offset:96
	s_waitcnt lgkmcnt(5)
	v_mfma_f32_32x32x16_bf16 v[80:95], v[186:189], v[112:115], 0
	ds_read_b128 v[210:213], v252 offset:12896
	s_waitcnt lgkmcnt(5)
	v_mfma_f32_32x32x16_bf16 v[64:79], v[190:193], v[116:119], v[64:79]
	ds_read_b128 v[182:185], v252 offset:128
	s_waitcnt lgkmcnt(5)
	v_mfma_f32_32x32x16_bf16 v[80:95], v[194:197], v[116:119], v[80:95]
	ds_read_b128 v[186:189], v252 offset:12928
	s_waitcnt lgkmcnt(5)
	v_mfma_f32_32x32x16_bf16 v[64:79], v[198:201], v[120:123], v[64:79]
	ds_read_b128 v[190:193], v252 offset:160
	s_waitcnt lgkmcnt(5)
	v_mfma_f32_32x32x16_bf16 v[80:95], v[202:205], v[120:123], v[80:95]
	ds_read_b128 v[194:197], v252 offset:12960
	s_waitcnt lgkmcnt(5)
	v_mfma_f32_32x32x16_bf16 v[64:79], v[206:209], v[124:127], v[64:79]
	ds_read_b128 v[198:201], v252 offset:192
	s_waitcnt lgkmcnt(5)
	v_mfma_f32_32x32x16_bf16 v[80:95], v[210:213], v[124:127], v[80:95]
	ds_read_b128 v[202:205], v252 offset:12992
	s_waitcnt lgkmcnt(5)
	v_mfma_f32_32x32x16_bf16 v[64:79], v[182:185], v[128:131], v[64:79]
	ds_read_b128 v[206:209], v252 offset:224
	s_waitcnt lgkmcnt(5)
	v_mfma_f32_32x32x16_bf16 v[80:95], v[186:189], v[128:131], v[80:95]
	ds_read_b128 v[210:213], v252 offset:13024
	s_waitcnt lgkmcnt(5)
	v_mfma_f32_32x32x16_bf16 v[64:79], v[190:193], v[132:135], v[64:79]
	ds_read_b128 v[182:185], v252 offset:256
	s_waitcnt lgkmcnt(5)
	v_mfma_f32_32x32x16_bf16 v[80:95], v[194:197], v[132:135], v[80:95]
	ds_read_b128 v[186:189], v252 offset:13056
	s_waitcnt lgkmcnt(5)
	v_mfma_f32_32x32x16_bf16 v[64:79], v[198:201], v[136:139], v[64:79]
	ds_read_b128 v[190:193], v252 offset:288
	s_waitcnt lgkmcnt(5)
	v_mfma_f32_32x32x16_bf16 v[80:95], v[202:205], v[136:139], v[80:95]
	ds_read_b128 v[194:197], v252 offset:13088
	s_waitcnt lgkmcnt(5)
	v_mfma_f32_32x32x16_bf16 v[64:79], v[206:209], v[140:143], v[64:79]
	ds_read_b128 v[198:201], v252 offset:320
	s_waitcnt lgkmcnt(5)
	v_mfma_f32_32x32x16_bf16 v[80:95], v[210:213], v[140:143], v[80:95]
	ds_read_b128 v[202:205], v252 offset:13120
	s_waitcnt lgkmcnt(5)
	v_mfma_f32_32x32x16_bf16 v[64:79], v[182:185], v[144:147], v[64:79]
	ds_read_b128 v[206:209], v252 offset:352
	s_waitcnt lgkmcnt(5)
	v_mfma_f32_32x32x16_bf16 v[80:95], v[186:189], v[144:147], v[80:95]
	ds_read_b128 v[210:213], v252 offset:13152
	s_waitcnt lgkmcnt(5)
	v_mfma_f32_32x32x16_bf16 v[64:79], v[190:193], v[148:151], v[64:79]
	s_waitcnt lgkmcnt(4)
	v_mfma_f32_32x32x16_bf16 v[80:95], v[194:197], v[148:151], v[80:95]
	s_waitcnt lgkmcnt(3)
	v_mfma_f32_32x32x16_bf16 v[64:79], v[198:201], v[152:155], v[64:79]
	s_waitcnt lgkmcnt(2)
	v_mfma_f32_32x32x16_bf16 v[80:95], v[202:205], v[152:155], v[80:95]
	s_waitcnt lgkmcnt(1)
	v_mfma_f32_32x32x16_bf16 v[64:79], v[206:209], v[156:159], v[64:79]
	s_waitcnt lgkmcnt(0)
	v_mfma_f32_32x32x16_bf16 v[80:95], v[210:213], v[156:159], v[80:95]
	s_branch .Lad_x1_end
; #define LAS __attribute__((address_space(3)))
; DI unsigned pk2(float a, float b) { f32x2 v = {a, b}; bf16v2_t r = __builtin_convertvector(v, bf16v2_t); return __builtin_bit_cast(unsigned, r); }
; DI f32x16 mfma32(bf16x8 a, bf16x8 b, f32x16 c) { return __builtin_amdgcn_mfma_f32_32x32x16_bf16(a, b, c, 0, 0, 0); }
; template <int DQK, int KA8, int DV, bool BIAS, bool JOINT>
; DI void attn_core(LAS unsigned char* lds, const bf16_t* Qrow, const bf16_t* KpA, int ldkA, const bf16_t* KpB, int ldkB, const bf16_t* Vp, int ldv,
;                   int qb, int wid, int lane, const float* qng  , f32x16 (&O)[DV / 32]) {
;     ...
;     auto gload = [&](int kt) {
; #pragma unroll
;         for (int i = 0; i < NL; ++i) { const int c = tid + i * 512;
;             if (i * 512 < NKC) { const int row = c / KC, cc = c % KC;
;                 const bf16_t* src = (cc < KA8) ? KpA + (size_t)(kt * 64 + row) * ldkA + cc * 8 : KpB + (size_t)(kt * 64 + row) * ldkB + (cc - KA8) * 8;
;                 stg[i] = *(const u32x4*)src; }
;             else { const int c2 = c - NKC, row = c2 / VC, cc = c2 % VC; stg[i] = *(const u32x4*)(Vp + (size_t)(kt * 64 + row) * ldv + cc * 8); } }
;     };
;     auto lstore = [&](int buf) {
; #pragma unroll
;         for (int i = 0; i < NL; ++i) { const int c = tid + i * 512;
;             if (i * 512 < NKC) { const int row = c / KC, cc = c % KC; *(LAS u32x4*)(lds + buf * STG + row * KROW + cc * 16) = stg[i]; }
;             else { const int c2 = c - NKC, row = c2 / VC, cc = c2 % VC; *(LAS u32x4*)(lds + buf * STG + 64 * KROW + row * VROW + cc * 16) = stg[i]; } }
;     ...
;             for (int half = 0; half < 2; ++half)
; #pragma unroll
;                 for (int s = 0; s < 2; ++s) {
;                     const f32x16& S = half ? S1 : S0;
;                     u32x4 pw; pw.x = pk2(S[8 * s], S[8 * s + 1]); pw.y = pk2(S[8 * s + 2], S[8 * s + 3]); pw.z = pk2(S[8 * s + 4], S[8 * s + 5]); pw.w = pk2(S[8 * s + 6], S[8 * s + 7]);
;                     const bf16x8 pf = __builtin_bit_cast(bf16x8, pw);
;                     LAS unsigned char* vr = vb + vtr + (32 * half + 16 * s) * VROW;
; #pragma unroll
;                     for (int dt = 0; dt < DV / 32; ++dt) {
;                         const bf16x8 vf = cat4(trread(vr + 64 * dt), trread(vr + 8 * VROW + 64 * dt));
;                         O[dt] = mfma32(vf, pf, O[dt]);
;                     }
.Lad_x1_pv:
	ds_read_b64_tr_b16 v[182:183], v215 offset:0
	ds_read_b64_tr_b16 v[184:185], v215 offset:2560
	ds_read_b64_tr_b16 v[186:187], v215 offset:64
	ds_read_b64_tr_b16 v[188:189], v215 offset:2624
	ds_read_b64_tr_b16 v[190:191], v215 offset:128
	ds_read_b64_tr_b16 v[192:193], v215 offset:2688
	ds_read_b64_tr_b16 v[194:195], v215 offset:192
	ds_read_b64_tr_b16 v[196:197], v215 offset:2752
	ds_read_b64_tr_b16 v[198:199], v215 offset:5120
	ds_read_b64_tr_b16 v[200:201], v215 offset:7680
	ds_read_b64_tr_b16 v[202:203], v215 offset:5184
	ds_read_b64_tr_b16 v[204:205], v215 offset:7744
	s_waitcnt lgkmcnt(10)
	v_mfma_f32_32x32x16_bf16 v[0:15], v[182:185], v[96:99], v[0:15]
	ds_read_b64_tr_b16 v[206:207], v215 offset:5248
	ds_read_b64_tr_b16 v[208:209], v215 offset:7808
	s_waitcnt lgkmcnt(10)
	v_mfma_f32_32x32x16_bf16 v[16:31], v[186:189], v[96:99], v[16:31]
	ds_read_b64_tr_b16 v[210:211], v215 offset:5312
	ds_read_b64_tr_b16 v[212:213], v215 offset:7872
	s_waitcnt lgkmcnt(10)
	v_mfma_f32_32x32x16_bf16 v[32:47], v[190:193], v[96:99], v[32:47]
	ds_read_b64_tr_b16 v[182:183], v215 offset:10240
	ds_read_b64_tr_b16 v[184:185], v215 offset:12800
	s_waitcnt lgkmcnt(10)
	v_mfma_f32_32x32x16_bf16 v[48:63], v[194:197], v[96:99], v[48:63]
	s_waitcnt vmcnt(0)
	s_add_i32 s58, s59, 1
	s_cmp_lt_u32 s58, s17
	s_cbranch_scc0 .Lad_hv_6
	ds_write_b128 v216, v[160:163] offset:40960
	ds_write_b128 v216, v[164:167] offset:53760
	ds_write_b128 v217, v[168:171] offset:40960
.Lad_hv_6:
	ds_write_b128 v218, v[172:175] offset:20480
	ds_write_b128 v218, v[176:179] offset:30720
	ds_read_b64_tr_b16 v[186:187], v215 offset:10304
	ds_read_b64_tr_b16 v[188:189], v215 offset:12864
	s_waitcnt lgkmcnt(12)
	v_mfma_f32_32x32x16_bf16 v[0:15], v[198:201], v[100:103], v[0:15]
	ds_read_b64_tr_b16 v[190:191], v215 offset:10368
	ds_read_b64_tr_b16 v[192:193], v215 offset:12928
	s_waitcnt lgkmcnt(12)
	v_mfma_f32_32x32x16_bf16 v[16:31], v[202:205], v[100:103], v[16:31]
	ds_read_b64_tr_b16 v[194:195], v215 offset:10432
	ds_read_b64_tr_b16 v[196:197], v215 offset:12992
	s_waitcnt lgkmcnt(12)
	v_mfma_f32_32x32x16_bf16 v[32:47], v[206:209], v[100:103], v[32:47]
	ds_read_b64_tr_b16 v[198:199], v215 offset:15360
	ds_read_b64_tr_b16 v[200:201], v215 offset:17920
	s_waitcnt lgkmcnt(12)
	v_mfma_f32_32x32x16_bf16 v[48:63], v[210:213], v[100:103], v[48:63]
	ds_read_b64_tr_b16 v[202:203], v215 offset:15424
	ds_read_b64_tr_b16 v[204:205], v215 offset:17984
	s_waitcnt lgkmcnt(12)
	v_mfma_f32_32x32x16_bf16 v[0:15], v[182:185], v[104:107], v[0:15]
	ds_read_b64_tr_b16 v[206:207], v215 offset:15488
	ds_read_b64_tr_b16 v[208:209], v215 offset:18048
	s_waitcnt lgkmcnt(10)
	v_mfma_f32_32x32x16_bf16 v[16:31], v[186:189], v[104:107], v[16:31]
	ds_read_b64_tr_b16 v[210:211], v215 offset:15552
	ds_read_b64_tr_b16 v[212:213], v215 offset:18112
	s_waitcnt lgkmcnt(10)
	v_mfma_f32_32x32x16_bf16 v[32:47], v[190:193], v[104:107], v[32:47]
	s_waitcnt lgkmcnt(8)
	v_mfma_f32_32x32x16_bf16 v[48:63], v[194:197], v[104:107], v[48:63]
	s_waitcnt lgkmcnt(6)
	v_mfma_f32_32x32x16_bf16 v[0:15], v[198:201], v[108:111], v[0:15]
	s_waitcnt lgkmcnt(4)
	v_mfma_f32_32x32x16_bf16 v[16:31], v[202:205], v[108:111], v[16:31]
	s_waitcnt lgkmcnt(2)
	v_mfma_f32_32x32x16_bf16 v[32:47], v[206:209], v[108:111], v[32:47]
	s_waitcnt lgkmcnt(0)
	v_mfma_f32_32x32x16_bf16 v[48:63], v[210:213], v[108:111], v[48:63]
	s_branch .Lad_x1_end
.Lad_x1_none:
	s_waitcnt vmcnt(0)
	s_add_i32 s58, s59, 1
	s_cmp_lt_u32 s58, s17
	s_cbranch_scc0 .Lad_hv_7
	ds_write_b128 v216, v[160:163] offset:40960
	ds_write_b128 v216, v[164:167] offset:53760
	ds_write_b128 v217, v[168:171] offset:40960
.Lad_hv_7:
	ds_write_b128 v218, v[172:175] offset:20480
	ds_write_b128 v218, v[176:179] offset:30720
.Lad_x1_end:
	s_waitcnt lgkmcnt(0)
	s_barrier
	s_add_i32 s58, s59, 1
	s_cmp_lt_u32 s58, s17
	s_cbranch_scc0 .Lad_y1_nold
	global_load_dwordx4 v[172:175], v222, s[34:35]
	global_load_dwordx4 v[176:179], v223, s[34:35]
	s_add_u32 s34, s34, 0xe0000
	s_addc_u32 s35, s35, 0
	s_add_i32 s58, s59, 2
	s_cmp_lt_u32 s58, s17
	s_cbranch_scc0 .Lad_y1_nold
	global_load_dwordx4 v[160:163], v219, s[30:31]
	global_load_dwordx4 v[164:167], v220, s[30:31]
	global_load_dwordx4 v[168:171], v221, s[36:37]
	s_add_u32 s30, s30, 0xe0000
	s_addc_u32 s31, s31, 0
	s_add_u32 s36, s36, 0x22000
	s_addc_u32 s37, s37, 0
; template <int DQK, int KA8, int DV, bool BIAS, bool JOINT>
; DI void attn_core(LAS unsigned char* lds, const bf16_t* Qrow, const bf16_t* KpA, int ldkA, const bf16_t* KpB, int ldkB, const bf16_t* Vp, int ldv,
;                   int qb, int wid, int lane, const float* qng  , f32x16 (&O)[DV / 32]) {
;     ...
;             if (mnz) {
; #pragma unroll
;                 for (int i = 0; i < 16; ++i) { S0[i] -= m; S1[i] -= m; }
;             }
;             float mx = fmaxf(S0[0], S1[0]);
; #pragma unroll
;             for (int i = 1; i < 16; ++i) mx = fmaxf(mx, fmaxf(S0[i], S1[i]));
;             mx = fmaxf(mx, __shfl_xor(mx, 32));
;             if (__any(mx > 64.f || (kt == 0 && mx < -64.f))) {
;                 const float dm = (mx > 64.f || (kt == 0 && mx < -64.f)) ? mx : 0.f, alpha = __builtin_amdgcn_exp2f(-dm); m += dm; mnz = true;
;                 l *= alpha;
; #pragma unroll
;                 for (int dt = 0; dt < DV / 32; ++dt) O[dt] *= alpha;
; #pragma unroll
;                 for (int i = 0; i < 16; ++i) { S0[i] -= dm; S1[i] -= dm; }
;             }
.Lad_y1_nold:
	s_cmp_gt_u32 s59, s25
	s_cbranch_scc1 .Lad_y1_end
	s_nop 15
	s_cmp_eq_u32 s40, 0
	s_cbranch_scc1 .Lad_y1_nosubm
	v_sub_f32_e32 v64, v64, v224
	v_sub_f32_e32 v65, v65, v224
	v_sub_f32_e32 v66, v66, v224
	v_sub_f32_e32 v67, v67, v224
	v_sub_f32_e32 v68, v68, v224
	v_sub_f32_e32 v69, v69, v224
	v_sub_f32_e32 v70, v70, v224
	v_sub_f32_e32 v71, v71, v224
	v_sub_f32_e32 v72, v72, v224
	v_sub_f32_e32 v73, v73, v224
	v_sub_f32_e32 v74, v74, v224
	v_sub_f32_e32 v75, v75, v224
	v_sub_f32_e32 v76, v76, v224
	v_sub_f32_e32 v77, v77, v224
	v_sub_f32_e32 v78, v78, v224
	v_sub_f32_e32 v79, v79, v224
	v_sub_f32_e32 v80, v80, v224
	v_sub_f32_e32 v81, v81, v224
	v_sub_f32_e32 v82, v82, v224
	v_sub_f32_e32 v83, v83, v224
	v_sub_f32_e32 v84, v84, v224
	v_sub_f32_e32 v85, v85, v224
	v_sub_f32_e32 v86, v86, v224
	v_sub_f32_e32 v87, v87, v224
	v_sub_f32_e32 v88, v88, v224
	v_sub_f32_e32 v89, v89, v224
	v_sub_f32_e32 v90, v90, v224
	v_sub_f32_e32 v91, v91, v224
	v_sub_f32_e32 v92, v92, v224
	v_sub_f32_e32 v93, v93, v224
	v_sub_f32_e32 v94, v94, v224
	v_sub_f32_e32 v95, v95, v224
.Lad_y1_nosubm:
	v_max3_f32 v229, v64, v65, v66
	v_max3_f32 v232, v67, v68, v69
	v_max3_f32 v233, v70, v71, v72
	v_max3_f32 v234, v73, v74, v75
	v_max3_f32 v229, v229, v76, v77
	v_max3_f32 v232, v232, v78, v79
	v_max3_f32 v233, v233, v80, v81
	v_max3_f32 v234, v234, v82, v83
	v_max3_f32 v229, v229, v84, v85
	v_max3_f32 v232, v232, v86, v87
	v_max3_f32 v233, v233, v88, v89
	v_max3_f32 v234, v234, v90, v91
	v_max3_f32 v229, v229, v92, v93
	v_max3_f32 v232, v232, v94, v95
	v_max3_f32 v229, v229, v232, v233
	v_max_f32_e32 v229, v229, v234
	v_mov_b32_e32 v230, v229
	v_mov_b32_e32 v231, v229
	s_nop 1
	v_permlane32_swap_b32_e32 v230, v231
	s_nop 1
	v_max_f32_e32 v229, v230, v231
	v_cmp_lt_f32_e32 vcc, 0x42800000, v229
	s_cmp_lg_u64 vcc, 0
	s_cbranch_scc0 .Lad_y1_noresc
	s_nop 3
	v_cndmask_b32_e32 v232, 0, v229, vcc
	v_exp_f32_e64 v233, -v232
	v_add_f32_e32 v224, v224, v232
	s_mov_b32 s40, 1
	v_mul_f32_e32 v225, v225, v233
	v_mul_f32_e32 v0, v0, v233
	v_mul_f32_e32 v1, v1, v233
	v_mul_f32_e32 v2, v2, v233
	v_mul_f32_e32 v3, v3, v233
	v_mul_f32_e32 v4, v4, v233
	v_mul_f32_e32 v5, v5, v233
	v_mul_f32_e32 v6, v6, v233
	v_mul_f32_e32 v7, v7, v233
	v_mul_f32_e32 v8, v8, v233
	v_mul_f32_e32 v9, v9, v233
	v_mul_f32_e32 v10, v10, v233
	v_mul_f32_e32 v11, v11, v233
	v_mul_f32_e32 v12, v12, v233
	v_mul_f32_e32 v13, v13, v233
	v_mul_f32_e32 v14, v14, v233
	v_mul_f32_e32 v15, v15, v233
	v_mul_f32_e32 v16, v16, v233
	v_mul_f32_e32 v17, v17, v233
	v_mul_f32_e32 v18, v18, v233
	v_mul_f32_e32 v19, v19, v233
	v_mul_f32_e32 v20, v20, v233
	v_mul_f32_e32 v21, v21, v233
	v_mul_f32_e32 v22, v22, v233
	v_mul_f32_e32 v23, v23, v233
	v_mul_f32_e32 v24, v24, v233
	v_mul_f32_e32 v25, v25, v233
	v_mul_f32_e32 v26, v26, v233
	v_mul_f32_e32 v27, v27, v233
	v_mul_f32_e32 v28, v28, v233
	v_mul_f32_e32 v29, v29, v233
	v_mul_f32_e32 v30, v30, v233
	v_mul_f32_e32 v31, v31, v233
	v_mul_f32_e32 v32, v32, v233
	v_mul_f32_e32 v33, v33, v233
	v_mul_f32_e32 v34, v34, v233
	v_mul_f32_e32 v35, v35, v233
	v_mul_f32_e32 v36, v36, v233
	v_mul_f32_e32 v37, v37, v233
	v_mul_f32_e32 v38, v38, v233
	v_mul_f32_e32 v39, v39, v233
	v_mul_f32_e32 v40, v40, v233
	v_mul_f32_e32 v41, v41, v233
	v_mul_f32_e32 v42, v42, v233
	v_mul_f32_e32 v43, v43, v233
	v_mul_f32_e32 v44, v44, v233
	v_mul_f32_e32 v45, v45, v233
	v_mul_f32_e32 v46, v46, v233
	v_mul_f32_e32 v47, v47, v233
	v_mul_f32_e32 v48, v48, v233
	v_mul_f32_e32 v49, v49, v233
	v_mul_f32_e32 v50, v50, v233
	v_mul_f32_e32 v51, v51, v233
	v_mul_f32_e32 v52, v52, v233
	v_mul_f32_e32 v53, v53, v233
	v_mul_f32_e32 v54, v54, v233
	v_mul_f32_e32 v55, v55, v233
	v_mul_f32_e32 v56, v56, v233
	v_mul_f32_e32 v57, v57, v233
	v_mul_f32_e32 v58, v58, v233
	v_mul_f32_e32 v59, v59, v233
	v_mul_f32_e32 v60, v60, v233
	v_mul_f32_e32 v61, v61, v233
	v_mul_f32_e32 v62, v62, v233
	v_mul_f32_e32 v63, v63, v233
	v_sub_f32_e32 v64, v64, v232
	v_sub_f32_e32 v65, v65, v232
	v_sub_f32_e32 v66, v66, v232
	v_sub_f32_e32 v67, v67, v232
	v_sub_f32_e32 v68, v68, v232
	v_sub_f32_e32 v69, v69, v232
	v_sub_f32_e32 v70, v70, v232
	v_sub_f32_e32 v71, v71, v232
	v_sub_f32_e32 v72, v72, v232
	v_sub_f32_e32 v73, v73, v232
	v_sub_f32_e32 v74, v74, v232
	v_sub_f32_e32 v75, v75, v232
	v_sub_f32_e32 v76, v76, v232
	v_sub_f32_e32 v77, v77, v232
	v_sub_f32_e32 v78, v78, v232
	v_sub_f32_e32 v79, v79, v232
	v_sub_f32_e32 v80, v80, v232
	v_sub_f32_e32 v81, v81, v232
	v_sub_f32_e32 v82, v82, v232
	v_sub_f32_e32 v83, v83, v232
	v_sub_f32_e32 v84, v84, v232
	v_sub_f32_e32 v85, v85, v232
	v_sub_f32_e32 v86, v86, v232
	v_sub_f32_e32 v87, v87, v232
	v_sub_f32_e32 v88, v88, v232
	v_sub_f32_e32 v89, v89, v232
	v_sub_f32_e32 v90, v90, v232
	v_sub_f32_e32 v91, v91, v232
	v_sub_f32_e32 v92, v92, v232
	v_sub_f32_e32 v93, v93, v232
	v_sub_f32_e32 v94, v94, v232
	v_sub_f32_e32 v95, v95, v232

; #define LAS __attribute__((address_space(3)))
; DI unsigned pk2(float a, float b) { f32x2 v = {a, b}; bf16v2_t r = __builtin_convertvector(v, bf16v2_t); return __builtin_bit_cast(unsigned, r); }
; DI f32x16 mfma32(bf16x8 a, bf16x8 b, f32x16 c) { return __builtin_amdgcn_mfma_f32_32x32x16_bf16(a, b, c, 0, 0, 0); }
; DI s16x4 trread(LAS unsigned char* p) { return __builtin_amdgcn_ds_read_tr16_b64_v4i16((LAS s16x4*)p); }
; DI bf16x8 cat4(s16x4 lo, s16x4 hi) { return __builtin_shufflevector(lo, hi, 0, 1, 2, 3, 4, 5, 6, 7); }
; template <int DQK, int KA8, int DV, bool BIAS, bool JOINT>
; DI void attn_core(LAS unsigned char* lds, const bf16_t* Qrow, const bf16_t* KpA, int ldkA, const bf16_t* KpB, int ldkB, const bf16_t* Vp, int ldv,
;                   int qb, int wid, int lane, const float* qng  , f32x16 (&O)[DV / 32]) {
;     ...
;             for (int half = 0; half < 2; ++half)
; #pragma unroll
;                 for (int s = 0; s < 2; ++s) {
;                     const f32x16& S = half ? S1 : S0;
;                     u32x4 pw; pw.x = pk2(S[8 * s], S[8 * s + 1]); pw.y = pk2(S[8 * s + 2], S[8 * s + 3]); pw.z = pk2(S[8 * s + 4], S[8 * s + 5]); pw.w = pk2(S[8 * s + 6], S[8 * s + 7]);
;                     const bf16x8 pf = __builtin_bit_cast(bf16x8, pw);
;                     LAS unsigned char* vr = vb + vtr + (32 * half + 16 * s) * VROW;
; #pragma unroll
;                     for (int dt = 0; dt < DV / 32; ++dt) {
;                         const bf16x8 vf = cat4(trread(vr + 64 * dt), trread(vr + 8 * VROW + 64 * dt));
;                         O[dt] = mfma32(vf, pf, O[dt]);
;                     }
.Lad_y1_end:
	s_barrier
	s_add_i32 s24, s24, 2
	s_cmp_lt_u32 s24, s17
	s_cbranch_scc1 .Lad_loop
	s_add_i32 s58, s25, 1
	s_cmp_ge_u32 s58, s17
	s_cbranch_scc0 .Lad_nofpv
	ds_read_b64_tr_b16 v[182:183], v215 offset:20480
	ds_read_b64_tr_b16 v[184:185], v215 offset:23040
	ds_read_b64_tr_b16 v[186:187], v215 offset:20544
	ds_read_b64_tr_b16 v[188:189], v215 offset:23104
	ds_read_b64_tr_b16 v[190:191], v215 offset:20608
	ds_read_b64_tr_b16 v[192:193], v215 offset:23168
	ds_read_b64_tr_b16 v[194:195], v215 offset:20672
	ds_read_b64_tr_b16 v[196:197], v215 offset:23232
	ds_read_b64_tr_b16 v[198:199], v215 offset:25600
	ds_read_b64_tr_b16 v[200:201], v215 offset:28160
	ds_read_b64_tr_b16 v[202:203], v215 offset:25664
	ds_read_b64_tr_b16 v[204:205], v215 offset:28224
	s_waitcnt lgkmcnt(10)
	v_mfma_f32_32x32x16_bf16 v[0:15], v[182:185], v[96:99], v[0:15]
	ds_read_b64_tr_b16 v[206:207], v215 offset:25728
	ds_read_b64_tr_b16 v[208:209], v215 offset:28288
	s_waitcnt lgkmcnt(10)
	v_mfma_f32_32x32x16_bf16 v[16:31], v[186:189], v[96:99], v[16:31]
	ds_read_b64_tr_b16 v[210:211], v215 offset:25792
	ds_read_b64_tr_b16 v[212:213], v215 offset:28352
	s_waitcnt lgkmcnt(10)
	v_mfma_f32_32x32x16_bf16 v[32:47], v[190:193], v[96:99], v[32:47]
	ds_read_b64_tr_b16 v[182:183], v215 offset:30720
	ds_read_b64_tr_b16 v[184:185], v215 offset:33280
	s_waitcnt lgkmcnt(10)
	v_mfma_f32_32x32x16_bf16 v[48:63], v[194:197], v[96:99], v[48:63]
	ds_read_b64_tr_b16 v[186:187], v215 offset:30784
	ds_read_b64_tr_b16 v[188:189], v215 offset:33344
	s_waitcnt lgkmcnt(10)
	v_mfma_f32_32x32x16_bf16 v[0:15], v[198:201], v[100:103], v[0:15]
	ds_read_b64_tr_b16 v[190:191], v215 offset:30848
	ds_read_b64_tr_b16 v[192:193], v215 offset:33408
	s_waitcnt lgkmcnt(10)
	v_mfma_f32_32x32x16_bf16 v[16:31], v[202:205], v[100:103], v[16:31]
	ds_read_b64_tr_b16 v[194:195], v215 offset:30912
	ds_read_b64_tr_b16 v[196:197], v215 offset:33472
	s_waitcnt lgkmcnt(10)
	v_mfma_f32_32x32x16_bf16 v[32:47], v[206:209], v[100:103], v[32:47]
	ds_read_b64_tr_b16 v[198:199], v215 offset:35840
	ds_read_b64_tr_b16 v[200:201], v215 offset:38400
	s_waitcnt lgkmcnt(10)
	v_mfma_f32_32x32x16_bf16 v[48:63], v[210:213], v[100:103], v[48:63]
	ds_read_b64_tr_b16 v[202:203], v215 offset:35904
	ds_read_b64_tr_b16 v[204:205], v215 offset:38464
	s_waitcnt lgkmcnt(10)
	v_mfma_f32_32x32x16_bf16 v[0:15], v[182:185], v[104:107], v[0:15]
	ds_read_b64_tr_b16 v[206:207], v215 offset:35968
	ds_read_b64_tr_b16 v[208:209], v215 offset:38528
	s_waitcnt lgkmcnt(10)
	v_mfma_f32_32x32x16_bf16 v[16:31], v[186:189], v[104:107], v[16:31]
	ds_read_b64_tr_b16 v[210:211], v215 offset:36032
	ds_read_b64_tr_b16 v[212:213], v215 offset:38592
	s_waitcnt lgkmcnt(10)
	v_mfma_f32_32x32x16_bf16 v[32:47], v[190:193], v[104:107], v[32:47]
	s_waitcnt lgkmcnt(8)
	v_mfma_f32_32x32x16_bf16 v[48:63], v[194:197], v[104:107], v[48:63]
	s_waitcnt lgkmcnt(6)
	v_mfma_f32_32x32x16_bf16 v[0:15], v[198:201], v[108:111], v[0:15]
	s_waitcnt lgkmcnt(4)
	v_mfma_f32_32x32x16_bf16 v[16:31], v[202:205], v[108:111], v[16:31]
	s_waitcnt lgkmcnt(2)
	v_mfma_f32_32x32x16_bf16 v[32:47], v[206:209], v[108:111], v[32:47]
	s_waitcnt lgkmcnt(0)
	v_mfma_f32_32x32x16_bf16 v[48:63], v[210:213], v[108:111], v[48:63]

; DI unsigned pk2(float a, float b) { f32x2 v = {a, b}; bf16v2_t r = __builtin_convertvector(v, bf16v2_t); return __builtin_bit_cast(unsigned, r); }
; DI float silu(float x) { return x / (1.f + __expf(-x)); }
; template <int DQK, int KA8, int DV, bool BIAS, bool JOINT>
; DI void attn_core(LAS unsigned char* lds, const bf16_t* Qrow, const bf16_t* KpA, int ldkA, const bf16_t* KpB, int ldkB, const bf16_t* Vp, int ldv,
;                   int qb, int wid, int lane, const float* qng  , f32x16 (&O)[DV / 32]) {
;     ...
;     l += __shfl_xor(l, 32);
;     const float il = 1.f / l;
; #pragma unroll
;     for (int dt = 0; dt < DV / 32; ++dt) O[dt] *= il;
; DI void phase_attn_d(const Params& p, LAS unsigned char* lds) {
;     ...
; #pragma unroll
;             for (int dt = 0; dt < 4; ++dt)
; #pragma unroll
;                 for (int g4 = 0; g4 < 4; ++g4) { const int dv = 32 * dt + 8 * g4 + 4 * hh2;
;                     const u32x2 gw = *(const u32x2*)(gb + tokq2 * DM + h * 128 + dv);
;                     const float g0 = __uint_as_float(gw.x << 16), g1 = __uint_as_float(gw.x & 0xffff0000u), g2 = __uint_as_float(gw.y << 16), g3 = __uint_as_float(gw.y & 0xffff0000u);
;                     u32x2 w; w.x = pk2(O[dt][4 * g4] * silu(g0), O[dt][4 * g4 + 1] * silu(g1)); w.y = pk2(O[dt][4 * g4 + 2] * silu(g2), O[dt][4 * g4 + 3] * silu(g3));
;                     *(u32x2*)(y + tokq2 * DM + h * 128 + dv) = w; }
.Lad_noea:
	global_load_dwordx2 v[182:183], v238, s[54:55] offset:0
	global_load_dwordx2 v[184:185], v238, s[54:55] offset:16
	global_load_dwordx2 v[186:187], v238, s[54:55] offset:32
	global_load_dwordx2 v[188:189], v238, s[54:55] offset:48
	global_load_dwordx2 v[190:191], v238, s[54:55] offset:64
	global_load_dwordx2 v[192:193], v238, s[54:55] offset:80
	global_load_dwordx2 v[194:195], v238, s[54:55] offset:96
	global_load_dwordx2 v[196:197], v238, s[54:55] offset:112
	global_load_dwordx2 v[198:199], v238, s[54:55] offset:128
	global_load_dwordx2 v[200:201], v238, s[54:55] offset:144
	global_load_dwordx2 v[202:203], v238, s[54:55] offset:160
	global_load_dwordx2 v[204:205], v238, s[54:55] offset:176
	global_load_dwordx2 v[206:207], v238, s[54:55] offset:192
	global_load_dwordx2 v[208:209], v238, s[54:55] offset:208
	global_load_dwordx2 v[210:211], v238, s[54:55] offset:224
	global_load_dwordx2 v[212:213], v238, s[54:55] offset:240
	s_nop 15
	v_mov_b32_e32 v230, v225
	v_mov_b32_e32 v231, v225
	s_nop 1
	v_permlane32_swap_b32_e32 v230, v231
	s_nop 1
	v_add_f32_e32 v225, v230, v231
	v_rcp_f32_e32 v229, v225
	s_nop 1
	v_mul_f32_e32 v0, v0, v229
	v_mul_f32_e32 v1, v1, v229
	v_mul_f32_e32 v2, v2, v229
	v_mul_f32_e32 v3, v3, v229
	v_mul_f32_e32 v4, v4, v229
	v_mul_f32_e32 v5, v5, v229
	v_mul_f32_e32 v6, v6, v229
	v_mul_f32_e32 v7, v7, v229
	v_mul_f32_e32 v8, v8, v229
	v_mul_f32_e32 v9, v9, v229
	v_mul_f32_e32 v10, v10, v229
	v_mul_f32_e32 v11, v11, v229
	v_mul_f32_e32 v12, v12, v229
	v_mul_f32_e32 v13, v13, v229
	v_mul_f32_e32 v14, v14, v229
	v_mul_f32_e32 v15, v15, v229
	v_mul_f32_e32 v16, v16, v229
	v_mul_f32_e32 v17, v17, v229
	v_mul_f32_e32 v18, v18, v229
	v_mul_f32_e32 v19, v19, v229
	v_mul_f32_e32 v20, v20, v229
	v_mul_f32_e32 v21, v21, v229
	v_mul_f32_e32 v22, v22, v229
	v_mul_f32_e32 v23, v23, v229
	v_mul_f32_e32 v24, v24, v229
	v_mul_f32_e32 v25, v25, v229
	v_mul_f32_e32 v26, v26, v229
	v_mul_f32_e32 v27, v27, v229
	v_mul_f32_e32 v28, v28, v229
	v_mul_f32_e32 v29, v29, v229
	v_mul_f32_e32 v30, v30, v229
	v_mul_f32_e32 v31, v31, v229
	v_mul_f32_e32 v32, v32, v229
	v_mul_f32_e32 v33, v33, v229
	v_mul_f32_e32 v34, v34, v229
	v_mul_f32_e32 v35, v35, v229
	v_mul_f32_e32 v36, v36, v229
	v_mul_f32_e32 v37, v37, v229
	v_mul_f32_e32 v38, v38, v229
	v_mul_f32_e32 v39, v39, v229
	v_mul_f32_e32 v40, v40, v229
	v_mul_f32_e32 v41, v41, v229
	v_mul_f32_e32 v42, v42, v229
	v_mul_f32_e32 v43, v43, v229
	v_mul_f32_e32 v44, v44, v229
	v_mul_f32_e32 v45, v45, v229
	v_mul_f32_e32 v46, v46, v229
	v_mul_f32_e32 v47, v47, v229
	v_mul_f32_e32 v48, v48, v229
	v_mul_f32_e32 v49, v49, v229
	v_mul_f32_e32 v50, v50, v229
	v_mul_f32_e32 v51, v51, v229
	v_mul_f32_e32 v52, v52, v229
	v_mul_f32_e32 v53, v53, v229
	v_mul_f32_e32 v54, v54, v229
	v_mul_f32_e32 v55, v55, v229
	v_mul_f32_e32 v56, v56, v229
	v_mul_f32_e32 v57, v57, v229
	v_mul_f32_e32 v58, v58, v229
	v_mul_f32_e32 v59, v59, v229
	v_mul_f32_e32 v60, v60, v229
	v_mul_f32_e32 v61, v61, v229
	v_mul_f32_e32 v62, v62, v229
	v_mul_f32_e32 v63, v63, v229
	s_waitcnt vmcnt(0)
	v_lshlrev_b32_e32 v243, 16, v182
	v_and_b32_e32 v244, 0xffff0000, v182
	v_lshlrev_b32_e32 v245, 16, v183
	v_and_b32_e32 v246, 0xffff0000, v183
	v_mul_f32_e32 v247, 0xbfb8aa3b, v243
	v_mul_f32_e32 v248, 0xbfb8aa3b, v244
	v_mul_f32_e32 v249, 0xbfb8aa3b, v245
	v_mul_f32_e32 v250, 0xbfb8aa3b, v246
	v_exp_f32_e32 v247, v247
	v_exp_f32_e32 v248, v248
	v_exp_f32_e32 v249, v249
	v_exp_f32_e32 v250, v250
	s_nop 0
	v_add_f32_e32 v247, 1.0, v247
	v_add_f32_e32 v248, 1.0, v248
	v_add_f32_e32 v249, 1.0, v249
	v_add_f32_e32 v250, 1.0, v250
	v_rcp_f32_e32 v247, v247
	v_rcp_f32_e32 v248, v248
	v_rcp_f32_e32 v249, v249
	v_rcp_f32_e32 v250, v250
	s_nop 0
	v_mul_f32_e32 v243, v243, v247
	v_mul_f32_e32 v244, v244, v248
	v_mul_f32_e32 v245, v245, v249
	v_mul_f32_e32 v246, v246, v250
	v_mul_f32_e32 v0, v0, v243
	v_mul_f32_e32 v1, v1, v244
	v_mul_f32_e32 v2, v2, v245
	v_mul_f32_e32 v3, v3, v246
	v_cvt_pk_bf16_f32 v182, v0, v1
	v_cvt_pk_bf16_f32 v183, v2, v3
	global_store_dwordx2 v238, v[182:183], s[54:55] offset:0
	v_lshlrev_b32_e32 v243, 16, v184
	v_and_b32_e32 v244, 0xffff0000, v184
	v_lshlrev_b32_e32 v245, 16, v185
	v_and_b32_e32 v246, 0xffff0000, v185
	v_mul_f32_e32 v247, 0xbfb8aa3b, v243
	v_mul_f32_e32 v248, 0xbfb8aa3b, v244
	v_mul_f32_e32 v249, 0xbfb8aa3b, v245
	v_mul_f32_e32 v250, 0xbfb8aa3b, v246
	v_exp_f32_e32 v247, v247
	v_exp_f32_e32 v248, v248
	v_exp_f32_e32 v249, v249
	v_exp_f32_e32 v250, v250
	s_nop 0
	v_add_f32_e32 v247, 1.0, v247
	v_add_f32_e32 v248, 1.0, v248
	v_add_f32_e32 v249, 1.0, v249
	v_add_f32_e32 v250, 1.0, v250
	v_rcp_f32_e32 v247, v247
	v_rcp_f32_e32 v248, v248
	v_rcp_f32_e32 v249, v249
	v_rcp_f32_e32 v250, v250
	s_nop 0
	v_mul_f32_e32 v243, v243, v247
	v_mul_f32_e32 v244, v244, v248
	v_mul_f32_e32 v245, v245, v249
	v_mul_f32_e32 v246, v246, v250
	v_mul_f32_e32 v4, v4, v243
	v_mul_f32_e32 v5, v5, v244
	v_mul_f32_e32 v6, v6, v245
	v_mul_f32_e32 v7, v7, v246
	v_cvt_pk_bf16_f32 v184, v4, v5
	v_cvt_pk_bf16_f32 v185, v6, v7
	global_store_dwordx2 v238, v[184:185], s[54:55] offset:16
	v_lshlrev_b32_e32 v243, 16, v186
	v_and_b32_e32 v244, 0xffff0000, v186
	v_lshlrev_b32_e32 v245, 16, v187
	v_and_b32_e32 v246, 0xffff0000, v187
	v_mul_f32_e32 v247, 0xbfb8aa3b, v243
	v_mul_f32_e32 v248, 0xbfb8aa3b, v244
	v_mul_f32_e32 v249, 0xbfb8aa3b, v245
	v_mul_f32_e32 v250, 0xbfb8aa3b, v246
	v_exp_f32_e32 v247, v247
	v_exp_f32_e32 v248, v248
	v_exp_f32_e32 v249, v249
	v_exp_f32_e32 v250, v250
	s_nop 0
	v_add_f32_e32 v247, 1.0, v247
	v_add_f32_e32 v248, 1.0, v248
	v_add_f32_e32 v249, 1.0, v249
	v_add_f32_e32 v250, 1.0, v250
	v_rcp_f32_e32 v247, v247
; DI unsigned pk2(float a, float b) { f32x2 v = {a, b}; bf16v2_t r = __builtin_convertvector(v, bf16v2_t); return __builtin_bit_cast(unsigned, r); }
; DI float silu(float x) { return x / (1.f + __expf(-x)); }
; DI void phase_attn_d(const Params& p, LAS unsigned char* lds) {
;     ...
; #pragma unroll
;             for (int dt = 0; dt < 4; ++dt)
; #pragma unroll
;                 for (int g4 = 0; g4 < 4; ++g4) { const int dv = 32 * dt + 8 * g4 + 4 * hh2;
;                     const u32x2 gw = *(const u32x2*)(gb + tokq2 * DM + h * 128 + dv);
;                     const float g0 = __uint_as_float(gw.x << 16), g1 = __uint_as_float(gw.x & 0xffff0000u), g2 = __uint_as_float(gw.y << 16), g3 = __uint_as_float(gw.y & 0xffff0000u);
;                     u32x2 w; w.x = pk2(O[dt][4 * g4] * silu(g0), O[dt][4 * g4 + 1] * silu(g1)); w.y = pk2(O[dt][4 * g4 + 2] * silu(g2), O[dt][4 * g4 + 3] * silu(g3));
;                     *(u32x2*)(y + tokq2 * DM + h * 128 + dv) = w; }
	v_rcp_f32_e32 v248, v248
	v_rcp_f32_e32 v249, v249
	v_rcp_f32_e32 v250, v250
	s_nop 0
	v_mul_f32_e32 v243, v243, v247
	v_mul_f32_e32 v244, v244, v248
	v_mul_f32_e32 v245, v245, v249
	v_mul_f32_e32 v246, v246, v250
	v_mul_f32_e32 v8, v8, v243
	v_mul_f32_e32 v9, v9, v244
	v_mul_f32_e32 v10, v10, v245
	v_mul_f32_e32 v11, v11, v246
	v_cvt_pk_bf16_f32 v186, v8, v9
	v_cvt_pk_bf16_f32 v187, v10, v11
	global_store_dwordx2 v238, v[186:187], s[54:55] offset:32
	v_lshlrev_b32_e32 v243, 16, v188
	v_and_b32_e32 v244, 0xffff0000, v188
	v_lshlrev_b32_e32 v245, 16, v189
	v_and_b32_e32 v246, 0xffff0000, v189
	v_mul_f32_e32 v247, 0xbfb8aa3b, v243
	v_mul_f32_e32 v248, 0xbfb8aa3b, v244
	v_mul_f32_e32 v249, 0xbfb8aa3b, v245
	v_mul_f32_e32 v250, 0xbfb8aa3b, v246
	v_exp_f32_e32 v247, v247
	v_exp_f32_e32 v248, v248
	v_exp_f32_e32 v249, v249
	v_exp_f32_e32 v250, v250
	s_nop 0
	v_add_f32_e32 v247, 1.0, v247
	v_add_f32_e32 v248, 1.0, v248
	v_add_f32_e32 v249, 1.0, v249
	v_add_f32_e32 v250, 1.0, v250
	v_rcp_f32_e32 v247, v247
	v_rcp_f32_e32 v248, v248
	v_rcp_f32_e32 v249, v249
	v_rcp_f32_e32 v250, v250
	s_nop 0
	v_mul_f32_e32 v243, v243, v247
	v_mul_f32_e32 v244, v244, v248
	v_mul_f32_e32 v245, v245, v249
	v_mul_f32_e32 v246, v246, v250
	v_mul_f32_e32 v12, v12, v243
	v_mul_f32_e32 v13, v13, v244
	v_mul_f32_e32 v14, v14, v245
	v_mul_f32_e32 v15, v15, v246
	v_cvt_pk_bf16_f32 v188, v12, v13
	v_cvt_pk_bf16_f32 v189, v14, v15
	global_store_dwordx2 v238, v[188:189], s[54:55] offset:48
	v_lshlrev_b32_e32 v243, 16, v190
	v_and_b32_e32 v244, 0xffff0000, v190
	v_lshlrev_b32_e32 v245, 16, v191
	v_and_b32_e32 v246, 0xffff0000, v191
	v_mul_f32_e32 v247, 0xbfb8aa3b, v243
	v_mul_f32_e32 v248, 0xbfb8aa3b, v244
	v_mul_f32_e32 v249, 0xbfb8aa3b, v245
	v_mul_f32_e32 v250, 0xbfb8aa3b, v246
	v_exp_f32_e32 v247, v247
	v_exp_f32_e32 v248, v248
	v_exp_f32_e32 v249, v249
	v_exp_f32_e32 v250, v250
	s_nop 0
	v_add_f32_e32 v247, 1.0, v247
	v_add_f32_e32 v248, 1.0, v248
	v_add_f32_e32 v249, 1.0, v249
	v_add_f32_e32 v250, 1.0, v250
	v_rcp_f32_e32 v247, v247
	v_rcp_f32_e32 v248, v248
	v_rcp_f32_e32 v249, v249
	v_rcp_f32_e32 v250, v250
	s_nop 0
	v_mul_f32_e32 v243, v243, v247
	v_mul_f32_e32 v244, v244, v248
	v_mul_f32_e32 v245, v245, v249
	v_mul_f32_e32 v246, v246, v250
	v_mul_f32_e32 v16, v16, v243
	v_mul_f32_e32 v17, v17, v244
	v_mul_f32_e32 v18, v18, v245
	v_mul_f32_e32 v19, v19, v246
	v_cvt_pk_bf16_f32 v190, v16, v17
	v_cvt_pk_bf16_f32 v191, v18, v19
	global_store_dwordx2 v238, v[190:191], s[54:55] offset:64
	v_lshlrev_b32_e32 v243, 16, v192
	v_and_b32_e32 v244, 0xffff0000, v192
	v_lshlrev_b32_e32 v245, 16, v193
	v_and_b32_e32 v246, 0xffff0000, v193
	v_mul_f32_e32 v247, 0xbfb8aa3b, v243
	v_mul_f32_e32 v248, 0xbfb8aa3b, v244
	v_mul_f32_e32 v249, 0xbfb8aa3b, v245
	v_mul_f32_e32 v250, 0xbfb8aa3b, v246
	v_exp_f32_e32 v247, v247
	v_exp_f32_e32 v248, v248
	v_exp_f32_e32 v249, v249
	v_exp_f32_e32 v250, v250
	s_nop 0
	v_add_f32_e32 v247, 1.0, v247
	v_add_f32_e32 v248, 1.0, v248
	v_add_f32_e32 v249, 1.0, v249
	v_add_f32_e32 v250, 1.0, v250
	v_rcp_f32_e32 v247, v247
	v_rcp_f32_e32 v248, v248
	v_rcp_f32_e32 v249, v249
	v_rcp_f32_e32 v250, v250
	s_nop 0
	v_mul_f32_e32 v243, v243, v247
	v_mul_f32_e32 v244, v244, v248
	v_mul_f32_e32 v245, v245, v249
	v_mul_f32_e32 v246, v246, v250
	v_mul_f32_e32 v20, v20, v243
	v_mul_f32_e32 v21, v21, v244
	v_mul_f32_e32 v22, v22, v245
	v_mul_f32_e32 v23, v23, v246
	v_cvt_pk_bf16_f32 v192, v20, v21
	v_cvt_pk_bf16_f32 v193, v22, v23
	global_store_dwordx2 v238, v[192:193], s[54:55] offset:80
	v_lshlrev_b32_e32 v243, 16, v194
	v_and_b32_e32 v244, 0xffff0000, v194
	v_lshlrev_b32_e32 v245, 16, v195
	v_and_b32_e32 v246, 0xffff0000, v195
	v_mul_f32_e32 v247, 0xbfb8aa3b, v243
	v_mul_f32_e32 v248, 0xbfb8aa3b, v244
	v_mul_f32_e32 v249, 0xbfb8aa3b, v245
	v_mul_f32_e32 v250, 0xbfb8aa3b, v246
	v_exp_f32_e32 v247, v247
	v_exp_f32_e32 v248, v248
	v_exp_f32_e32 v249, v249
	v_exp_f32_e32 v250, v250
	s_nop 0
	v_add_f32_e32 v247, 1.0, v247
	v_add_f32_e32 v248, 1.0, v248
	v_add_f32_e32 v249, 1.0, v249
	v_add_f32_e32 v250, 1.0, v250
	v_rcp_f32_e32 v247, v247
	v_rcp_f32_e32 v248, v248
	v_rcp_f32_e32 v249, v249
	v_rcp_f32_e32 v250, v250
	s_nop 0
	v_mul_f32_e32 v243, v243, v247
	v_mul_f32_e32 v244, v244, v248
	v_mul_f32_e32 v245, v245, v249
	v_mul_f32_e32 v246, v246, v250
	v_mul_f32_e32 v24, v24, v243
	v_mul_f32_e32 v25, v25, v244
	v_mul_f32_e32 v26, v26, v245
	v_mul_f32_e32 v27, v27, v246
	v_cvt_pk_bf16_f32 v194, v24, v25
	v_cvt_pk_bf16_f32 v195, v26, v27
	global_store_dwordx2 v238, v[194:195], s[54:55] offset:96
	v_lshlrev_b32_e32 v243, 16, v196
	v_and_b32_e32 v244, 0xffff0000, v196
	v_lshlrev_b32_e32 v245, 16, v197
	v_and_b32_e32 v246, 0xffff0000, v197
	v_mul_f32_e32 v247, 0xbfb8aa3b, v243
	v_mul_f32_e32 v248, 0xbfb8aa3b, v244
	v_mul_f32_e32 v249, 0xbfb8aa3b, v245
	v_mul_f32_e32 v250, 0xbfb8aa3b, v246
	v_exp_f32_e32 v247, v247
	v_exp_f32_e32 v248, v248
	v_exp_f32_e32 v249, v249
	v_exp_f32_e32 v250, v250
	s_nop 0
	v_add_f32_e32 v247, 1.0, v247
	v_add_f32_e32 v248, 1.0, v248
	v_add_f32_e32 v249, 1.0, v249
	v_add_f32_e32 v250, 1.0, v250
	v_rcp_f32_e32 v247, v247
	v_rcp_f32_e32 v248, v248
	v_rcp_f32_e32 v249, v249
	v_rcp_f32_e32 v250, v250
	s_nop 0
	v_mul_f32_e32 v243, v243, v247
	v_mul_f32_e32 v244, v244, v248
	v_mul_f32_e32 v245, v245, v249
	v_mul_f32_e32 v246, v246, v250
	v_mul_f32_e32 v28, v28, v243
	v_mul_f32_e32 v29, v29, v244
	v_mul_f32_e32 v30, v30, v245
	v_mul_f32_e32 v31, v31, v246
	v_cvt_pk_bf16_f32 v196, v28, v29
	v_cvt_pk_bf16_f32 v197, v30, v31
	global_store_dwordx2 v238, v[196:197], s[54:55] offset:112
	v_lshlrev_b32_e32 v243, 16, v198
	v_and_b32_e32 v244, 0xffff0000, v198
; DI unsigned pk2(float a, float b) { f32x2 v = {a, b}; bf16v2_t r = __builtin_convertvector(v, bf16v2_t); return __builtin_bit_cast(unsigned, r); }
; DI float silu(float x) { return x / (1.f + __expf(-x)); }
; DI void phase_attn_d(const Params& p, LAS unsigned char* lds) {
;     ...
; #pragma unroll
;             for (int dt = 0; dt < 4; ++dt)
; #pragma unroll
;                 for (int g4 = 0; g4 < 4; ++g4) { const int dv = 32 * dt + 8 * g4 + 4 * hh2;
;                     const u32x2 gw = *(const u32x2*)(gb + tokq2 * DM + h * 128 + dv);
;                     const float g0 = __uint_as_float(gw.x << 16), g1 = __uint_as_float(gw.x & 0xffff0000u), g2 = __uint_as_float(gw.y << 16), g3 = __uint_as_float(gw.y & 0xffff0000u);
;                     u32x2 w; w.x = pk2(O[dt][4 * g4] * silu(g0), O[dt][4 * g4 + 1] * silu(g1)); w.y = pk2(O[dt][4 * g4 + 2] * silu(g2), O[dt][4 * g4 + 3] * silu(g3));
;                     *(u32x2*)(y + tokq2 * DM + h * 128 + dv) = w; }
	v_lshlrev_b32_e32 v245, 16, v199
	v_and_b32_e32 v246, 0xffff0000, v199
	v_mul_f32_e32 v247, 0xbfb8aa3b, v243
	v_mul_f32_e32 v248, 0xbfb8aa3b, v244
	v_mul_f32_e32 v249, 0xbfb8aa3b, v245
	v_mul_f32_e32 v250, 0xbfb8aa3b, v246
	v_exp_f32_e32 v247, v247
	v_exp_f32_e32 v248, v248
	v_exp_f32_e32 v249, v249
	v_exp_f32_e32 v250, v250
	s_nop 0
	v_add_f32_e32 v247, 1.0, v247
	v_add_f32_e32 v248, 1.0, v248
	v_add_f32_e32 v249, 1.0, v249
	v_add_f32_e32 v250, 1.0, v250
	v_rcp_f32_e32 v247, v247
	v_rcp_f32_e32 v248, v248
	v_rcp_f32_e32 v249, v249
	v_rcp_f32_e32 v250, v250
	s_nop 0
	v_mul_f32_e32 v243, v243, v247
	v_mul_f32_e32 v244, v244, v248
	v_mul_f32_e32 v245, v245, v249
	v_mul_f32_e32 v246, v246, v250
	v_mul_f32_e32 v32, v32, v243
	v_mul_f32_e32 v33, v33, v244
	v_mul_f32_e32 v34, v34, v245
	v_mul_f32_e32 v35, v35, v246
	v_cvt_pk_bf16_f32 v198, v32, v33
	v_cvt_pk_bf16_f32 v199, v34, v35
	global_store_dwordx2 v238, v[198:199], s[54:55] offset:128
	v_lshlrev_b32_e32 v243, 16, v200
	v_and_b32_e32 v244, 0xffff0000, v200
	v_lshlrev_b32_e32 v245, 16, v201
	v_and_b32_e32 v246, 0xffff0000, v201
	v_mul_f32_e32 v247, 0xbfb8aa3b, v243
	v_mul_f32_e32 v248, 0xbfb8aa3b, v244
	v_mul_f32_e32 v249, 0xbfb8aa3b, v245
	v_mul_f32_e32 v250, 0xbfb8aa3b, v246
	v_exp_f32_e32 v247, v247
	v_exp_f32_e32 v248, v248
	v_exp_f32_e32 v249, v249
	v_exp_f32_e32 v250, v250
	s_nop 0
	v_add_f32_e32 v247, 1.0, v247
	v_add_f32_e32 v248, 1.0, v248
	v_add_f32_e32 v249, 1.0, v249
	v_add_f32_e32 v250, 1.0, v250
	v_rcp_f32_e32 v247, v247
	v_rcp_f32_e32 v248, v248
	v_rcp_f32_e32 v249, v249
	v_rcp_f32_e32 v250, v250
	s_nop 0
	v_mul_f32_e32 v243, v243, v247
	v_mul_f32_e32 v244, v244, v248
	v_mul_f32_e32 v245, v245, v249
	v_mul_f32_e32 v246, v246, v250
	v_mul_f32_e32 v36, v36, v243
	v_mul_f32_e32 v37, v37, v244
	v_mul_f32_e32 v38, v38, v245
	v_mul_f32_e32 v39, v39, v246
	v_cvt_pk_bf16_f32 v200, v36, v37
	v_cvt_pk_bf16_f32 v201, v38, v39
	global_store_dwordx2 v238, v[200:201], s[54:55] offset:144
	v_lshlrev_b32_e32 v243, 16, v202
	v_and_b32_e32 v244, 0xffff0000, v202
	v_lshlrev_b32_e32 v245, 16, v203
	v_and_b32_e32 v246, 0xffff0000, v203
	v_mul_f32_e32 v247, 0xbfb8aa3b, v243
	v_mul_f32_e32 v248, 0xbfb8aa3b, v244
	v_mul_f32_e32 v249, 0xbfb8aa3b, v245
	v_mul_f32_e32 v250, 0xbfb8aa3b, v246
	v_exp_f32_e32 v247, v247
	v_exp_f32_e32 v248, v248
	v_exp_f32_e32 v249, v249
	v_exp_f32_e32 v250, v250
	s_nop 0
	v_add_f32_e32 v247, 1.0, v247
	v_add_f32_e32 v248, 1.0, v248
	v_add_f32_e32 v249, 1.0, v249
	v_add_f32_e32 v250, 1.0, v250
	v_rcp_f32_e32 v247, v247
	v_rcp_f32_e32 v248, v248
	v_rcp_f32_e32 v249, v249
	v_rcp_f32_e32 v250, v250
	s_nop 0
	v_mul_f32_e32 v243, v243, v247
	v_mul_f32_e32 v244, v244, v248
	v_mul_f32_e32 v245, v245, v249
	v_mul_f32_e32 v246, v246, v250
	v_mul_f32_e32 v40, v40, v243
	v_mul_f32_e32 v41, v41, v244
	v_mul_f32_e32 v42, v42, v245
	v_mul_f32_e32 v43, v43, v246
	v_cvt_pk_bf16_f32 v202, v40, v41
	v_cvt_pk_bf16_f32 v203, v42, v43
	global_store_dwordx2 v238, v[202:203], s[54:55] offset:160
	v_lshlrev_b32_e32 v243, 16, v204
	v_and_b32_e32 v244, 0xffff0000, v204
	v_lshlrev_b32_e32 v245, 16, v205
	v_and_b32_e32 v246, 0xffff0000, v205
	v_mul_f32_e32 v247, 0xbfb8aa3b, v243
	v_mul_f32_e32 v248, 0xbfb8aa3b, v244
	v_mul_f32_e32 v249, 0xbfb8aa3b, v245
	v_mul_f32_e32 v250, 0xbfb8aa3b, v246
	v_exp_f32_e32 v247, v247
	v_exp_f32_e32 v248, v248
	v_exp_f32_e32 v249, v249
	v_exp_f32_e32 v250, v250
	s_nop 0
	v_add_f32_e32 v247, 1.0, v247
	v_add_f32_e32 v248, 1.0, v248
	v_add_f32_e32 v249, 1.0, v249
	v_add_f32_e32 v250, 1.0, v250
	v_rcp_f32_e32 v247, v247
	v_rcp_f32_e32 v248, v248
	v_rcp_f32_e32 v249, v249
	v_rcp_f32_e32 v250, v250
	s_nop 0
	v_mul_f32_e32 v243, v243, v247
	v_mul_f32_e32 v244, v244, v248
	v_mul_f32_e32 v245, v245, v249
	v_mul_f32_e32 v246, v246, v250
	v_mul_f32_e32 v44, v44, v243
	v_mul_f32_e32 v45, v45, v244
	v_mul_f32_e32 v46, v46, v245
	v_mul_f32_e32 v47, v47, v246
	v_cvt_pk_bf16_f32 v204, v44, v45
	v_cvt_pk_bf16_f32 v205, v46, v47
	global_store_dwordx2 v238, v[204:205], s[54:55] offset:176
	v_lshlrev_b32_e32 v243, 16, v206
	v_and_b32_e32 v244, 0xffff0000, v206
	v_lshlrev_b32_e32 v245, 16, v207
	v_and_b32_e32 v246, 0xffff0000, v207
	v_mul_f32_e32 v247, 0xbfb8aa3b, v243
	v_mul_f32_e32 v248, 0xbfb8aa3b, v244
	v_mul_f32_e32 v249, 0xbfb8aa3b, v245
	v_mul_f32_e32 v250, 0xbfb8aa3b, v246
	v_exp_f32_e32 v247, v247
	v_exp_f32_e32 v248, v248
	v_exp_f32_e32 v249, v249
	v_exp_f32_e32 v250, v250
	s_nop 0
	v_add_f32_e32 v247, 1.0, v247
	v_add_f32_e32 v248, 1.0, v248
	v_add_f32_e32 v249, 1.0, v249
	v_add_f32_e32 v250, 1.0, v250
	v_rcp_f32_e32 v247, v247
	v_rcp_f32_e32 v248, v248
	v_rcp_f32_e32 v249, v249
	v_rcp_f32_e32 v250, v250
	s_nop 0
	v_mul_f32_e32 v243, v243, v247
	v_mul_f32_e32 v244, v244, v248
	v_mul_f32_e32 v245, v245, v249
	v_mul_f32_e32 v246, v246, v250
	v_mul_f32_e32 v48, v48, v243
	v_mul_f32_e32 v49, v49, v244
	v_mul_f32_e32 v50, v50, v245
; DI unsigned pk2(float a, float b) { f32x2 v = {a, b}; bf16v2_t r = __builtin_convertvector(v, bf16v2_t); return __builtin_bit_cast(unsigned, r); }
; DI float silu(float x) { return x / (1.f + __expf(-x)); }
; DI void phase_attn_d(const Params& p, LAS unsigned char* lds) {
;     ...
;     for (int pr = blockIdx.x; pr < 512; pr += gridDim.x) {
;         const int bi = pr & 255, bh = (gridDim.x == 256) ? (bi & 7) + 8 * (bi >> 6) + 32 * (pr >> 8) : pr >> 3, j = (gridDim.x == 256) ? (bi >> 3) & 7 : pr & 7, b = bh >> 4, h = bh & 15;
;         for (int half = 0; half < 2; ++half) {
;             const int qb = half ? 15 - j : j;
;     ...
; #pragma unroll
;             for (int dt = 0; dt < 4; ++dt)
; #pragma unroll
;                 for (int g4 = 0; g4 < 4; ++g4) { const int dv = 32 * dt + 8 * g4 + 4 * hh2;
;                     const u32x2 gw = *(const u32x2*)(gb + tokq2 * DM + h * 128 + dv);
;                     const float g0 = __uint_as_float(gw.x << 16), g1 = __uint_as_float(gw.x & 0xffff0000u), g2 = __uint_as_float(gw.y << 16), g3 = __uint_as_float(gw.y & 0xffff0000u);
;                     u32x2 w; w.x = pk2(O[dt][4 * g4] * silu(g0), O[dt][4 * g4 + 1] * silu(g1)); w.y = pk2(O[dt][4 * g4 + 2] * silu(g2), O[dt][4 * g4 + 3] * silu(g3));
;                     *(u32x2*)(y + tokq2 * DM + h * 128 + dv) = w; }
	v_mul_f32_e32 v51, v51, v246
	v_cvt_pk_bf16_f32 v206, v48, v49
	v_cvt_pk_bf16_f32 v207, v50, v51
	global_store_dwordx2 v238, v[206:207], s[54:55] offset:192
	v_lshlrev_b32_e32 v243, 16, v208
	v_and_b32_e32 v244, 0xffff0000, v208
	v_lshlrev_b32_e32 v245, 16, v209
	v_and_b32_e32 v246, 0xffff0000, v209
	v_mul_f32_e32 v247, 0xbfb8aa3b, v243
	v_mul_f32_e32 v248, 0xbfb8aa3b, v244
	v_mul_f32_e32 v249, 0xbfb8aa3b, v245
	v_mul_f32_e32 v250, 0xbfb8aa3b, v246
	v_exp_f32_e32 v247, v247
	v_exp_f32_e32 v248, v248
	v_exp_f32_e32 v249, v249
	v_exp_f32_e32 v250, v250
	s_nop 0
	v_add_f32_e32 v247, 1.0, v247
	v_add_f32_e32 v248, 1.0, v248
	v_add_f32_e32 v249, 1.0, v249
	v_add_f32_e32 v250, 1.0, v250
	v_rcp_f32_e32 v247, v247
	v_rcp_f32_e32 v248, v248
	v_rcp_f32_e32 v249, v249
	v_rcp_f32_e32 v250, v250
	s_nop 0
	v_mul_f32_e32 v243, v243, v247
	v_mul_f32_e32 v244, v244, v248
	v_mul_f32_e32 v245, v245, v249
	v_mul_f32_e32 v246, v246, v250
	v_mul_f32_e32 v52, v52, v243
	v_mul_f32_e32 v53, v53, v244
	v_mul_f32_e32 v54, v54, v245
	v_mul_f32_e32 v55, v55, v246
	v_cvt_pk_bf16_f32 v208, v52, v53
	v_cvt_pk_bf16_f32 v209, v54, v55
	global_store_dwordx2 v238, v[208:209], s[54:55] offset:208
	v_lshlrev_b32_e32 v243, 16, v210
	v_and_b32_e32 v244, 0xffff0000, v210
	v_lshlrev_b32_e32 v245, 16, v211
	v_and_b32_e32 v246, 0xffff0000, v211
	v_mul_f32_e32 v247, 0xbfb8aa3b, v243
	v_mul_f32_e32 v248, 0xbfb8aa3b, v244
	v_mul_f32_e32 v249, 0xbfb8aa3b, v245
	v_mul_f32_e32 v250, 0xbfb8aa3b, v246
	v_exp_f32_e32 v247, v247
	v_exp_f32_e32 v248, v248
	v_exp_f32_e32 v249, v249
	v_exp_f32_e32 v250, v250
	s_nop 0
	v_add_f32_e32 v247, 1.0, v247
	v_add_f32_e32 v248, 1.0, v248
	v_add_f32_e32 v249, 1.0, v249
	v_add_f32_e32 v250, 1.0, v250
	v_rcp_f32_e32 v247, v247
	v_rcp_f32_e32 v248, v248
	v_rcp_f32_e32 v249, v249
	v_rcp_f32_e32 v250, v250
	s_nop 0
	v_mul_f32_e32 v243, v243, v247
	v_mul_f32_e32 v244, v244, v248
	v_mul_f32_e32 v245, v245, v249
	v_mul_f32_e32 v246, v246, v250
	v_mul_f32_e32 v56, v56, v243
	v_mul_f32_e32 v57, v57, v244
	v_mul_f32_e32 v58, v58, v245
	v_mul_f32_e32 v59, v59, v246
	v_cvt_pk_bf16_f32 v210, v56, v57
	v_cvt_pk_bf16_f32 v211, v58, v59
	global_store_dwordx2 v238, v[210:211], s[54:55] offset:224
	v_lshlrev_b32_e32 v243, 16, v212
	v_and_b32_e32 v244, 0xffff0000, v212
	v_lshlrev_b32_e32 v245, 16, v213
	v_and_b32_e32 v246, 0xffff0000, v213
	v_mul_f32_e32 v247, 0xbfb8aa3b, v243
	v_mul_f32_e32 v248, 0xbfb8aa3b, v244
	v_mul_f32_e32 v249, 0xbfb8aa3b, v245
	v_mul_f32_e32 v250, 0xbfb8aa3b, v246
	v_exp_f32_e32 v247, v247
	v_exp_f32_e32 v248, v248
	v_exp_f32_e32 v249, v249
	v_exp_f32_e32 v250, v250
	s_nop 0
	v_add_f32_e32 v247, 1.0, v247
	v_add_f32_e32 v248, 1.0, v248
	v_add_f32_e32 v249, 1.0, v249
	v_add_f32_e32 v250, 1.0, v250
	v_rcp_f32_e32 v247, v247
	v_rcp_f32_e32 v248, v248
	v_rcp_f32_e32 v249, v249
	v_rcp_f32_e32 v250, v250
	s_nop 0
	v_mul_f32_e32 v243, v243, v247
	v_mul_f32_e32 v244, v244, v248
	v_mul_f32_e32 v245, v245, v249
	v_mul_f32_e32 v246, v246, v250
	v_mul_f32_e32 v60, v60, v243
	v_mul_f32_e32 v61, v61, v244
	v_mul_f32_e32 v62, v62, v245
	v_mul_f32_e32 v63, v63, v246
	v_cvt_pk_bf16_f32 v212, v60, v61
	v_cvt_pk_bf16_f32 v213, v62, v63
	global_store_dwordx2 v238, v[212:213], s[54:55] offset:240
	s_add_i32 s15, s15, 1
	s_cmp_lt_u32 s15, 2
	s_cbranch_scc1 .Lad_half
	s_add_i32 s14, s14, s18
	s_branch .Lad_unit
.Lad_done:
.LBB0_1625:
	s_waitcnt vmcnt(0)
	v_mov_b32_e32 v0, v181
	s_barrier
	s_nop 0
	v_cmp_eq_u32_e32 vcc, 0, v0
	s_and_saveexec_b64 s[6:7], vcc
	s_cbranch_execz .LBB0_1677
	s_add_i32 s8, 0, 0x20400
	v_mov_b32_e32 v0, s8
	s_getreg_b32 s3, hwreg(HW_REG_XCC_ID, 0, 4)
	s_waitcnt vmcnt(0) expcnt(0) lgkmcnt(0)
	ds_read_b32 v2, v0
	s_add_i32 s8, 0, 0x20404
	v_mov_b32_e32 v0, s8
	ds_read_b32 v0, v0
	s_and_b32 s3, s3, 15
	s_waitcnt lgkmcnt(1)
	v_cmp_ne_u32_e32 vcc, 0, v2
	s_cbranch_vccnz .LBB0_1641
	s_add_u32 s8, s20, 0x1ff00200
	s_addc_u32 s9, s21, 0
	s_add_u32 s10, s20, 0x1ff00400
	s_addc_u32 s11, s21, 0
	s_add_u32 s12, s20, 0x1ff00500
	s_addc_u32 s13, s21, 0
	s_add_u32 s14, s20, 0x1ff00600
	s_addc_u32 s15, s21, 0
	s_add_u32 s16, s20, 0x1ff00700
	s_addc_u32 s17, s21, 0
	s_add_u32 s24, s20, 0x1ff00800
	s_addc_u32 s25, s21, 0
	s_add_u32 s26, s20, 0x1ff00900
	s_addc_u32 s27, s21, 0
	s_add_u32 s28, s20, 0x1ff00a00
	s_addc_u32 s29, s21, 0
	s_add_u32 s30, s20, 0x1ff00b00
	s_addc_u32 s31, s21, 0
	s_add_u32 s34, s20, 0x1ff00c00
	s_addc_u32 s35, s21, 0
	s_add_u32 s36, s20, 0x1ff00d00
	s_addc_u32 s37, s21, 0
	s_add_u32 s38, s20, 0x1ff00e00
	s_addc_u32 s39, s21, 0
	s_add_u32 s40, s20, 0x1ff00f00
	s_addc_u32 s41, s21, 0
	s_add_u32 s42, s20, 0x1ff01000
	s_addc_u32 s43, s21, 0
	s_add_u32 s44, s20, 0x1ff01100
	s_addc_u32 s45, s21, 0
	s_add_u32 s46, s20, 0x1ff01200
	s_addc_u32 s47, s21, 0
	s_mul_i32 s19, s19, s33
	s_add_u32 s48, s20, 0x1ff01300
	s_mul_i32 s19, s19, s18
	s_addc_u32 s49, s21, 0
	s_mov_b32 s33, 1
	v_mov_b32_e32 v16, 0
	s_branch .LBB0_1629
